# attention A prologue: dead mask precompute removed; up-proj epilogue: conv weight loads issued before the LDS exchange
# baseline (speedup 1.0000x reference)
; #define LAS __attribute__((address_space(3)))
; __device__ __forceinline__ int fresh_tid() { int t = threadIdx.x; asm volatile("" : "+v"(t)); return t; }
; #define ATA_LOAD(c_) do { _Pragma("unroll") for (int it = 0; it < 4; ++it) { const size_t t_ = tok0 + (size_t)((n - 1 + (c_)) * 128 + srr + 32 * it) * d + r; \
;         kreg[it] = *(const u32x4*)(kbase + t_ * QKVW + sch * 8); vreg[it] = *(const u32x4*)(vbase + t_ * QKVW + sch * 8); } } while (0)
; __device__ __forceinline__ void attn_a_unit(LAS unsigned char* lds, bf16_t* QKV, float* LSE, int unit) {
;     ...
;     const int tid = fresh_tid(), wid = tid >> 6, lane = tid & 63, fr = lane & 15, fq = lane >> 4;
;     const int b = unit / 1536; const int rem = unit % 1536; const int hh = rem >> 7; const int w = rem & 127;
;     const int g = hh >> 2, dl = 2 * g, d = 1 << dl, nbl = 7 - dl;
;     const int r = w >> nbl, n = w & ((1 << nbl) - 1);
;     const size_t tok0 = (size_t)b * SEQ;
;     const bf16_t* kbase = QKV + 1536 + hh * 128; const bf16_t* vbase = QKV + 3072 + hh * 128;
;     const int qi = wid * 16 + fr;
;     const LAS bf16_t* vsw[2] = {Vt + fr * VT_PITCH + 4 * (fq ^ (fr >> 3)), Vt + fr * VT_PITCH + 4 * (fq ^ (2 + (fr >> 3)))};
;     const size_t tq = tok0 + (size_t)(n * 128 + qi) * d + r;
;     bf16x8 qf[4];
; #pragma unroll
;     for (int ds = 0; ds < 4; ++ds) qf[ds] = *(const bf16x8*)(QKV + tq * QKVW + hh * 128 + ds * 32 + fq * 8);
;     f32x4 o[8];
; #pragma unroll
;     for (int i = 0; i < 8; ++i) o[i] = (f32x4){0.f, 0.f, 0.f, 0.f};
;     constexpr float LOG2E = 1.4426950408889634f;
;     const float sd2 = exp2f(-8.0f * (float)(hh + 1) / 12.0f) * (float)d * LOG2E;
;     const int dq = qi - 4 * fq;
;     float m_run = -1e30f, l_run = 0.f;
;     u32x4 kreg[4], vreg[4];
;     const int srr = tid >> 4, sch = tid & 15;
;     ...
;     ATA_LOAD(1);
.LBB0_199:
	s_mul_hi_i32 s0, s75, 0x2aaaaaab
	s_lshr_b32 s1, s0, 31
	s_ashr_i32 s0, s0, 8
	s_add_i32 s0, s0, s1
	s_mul_i32 s1, s0, 0x600
	s_sub_i32 s8, s75, s1
	s_ashr_i32 s4, s8, 9
	v_writelane_b32 v251, s75, 48
	s_mov_b32 s2, s4
	v_writelane_b32 v251, s2, 49
	s_waitcnt vmcnt(15)
	v_mov_b32_e32 v16, v230
	s_and_b32 s1, s8, 0x7f
	v_writelane_b32 v251, s3, 50
	s_lshl_b32 s2, s4, 1
	s_lshr_b32 s3, s1, 3
	s_and_b32 s1, s1, 7
	s_lshl_b32 s1, s1, 4
	s_or_b32 s1, s1, s3
	s_sub_i32 s3, 7, s2
	v_ashrrev_i32_e32 v1, 2, v16
	v_lshrrev_b32_e32 v0, 4, v16
	s_lshr_b32 s6, s1, s3
	s_lshl_b32 s3, -1, s3
	v_bfi_b32 v59, -16, v1, v16
	v_bfe_u32 v1, v16, 3, 1
	v_bfe_u32 v101, v16, 4, 2
	s_andn2_b32 s3, s1, s3
	v_bitop3_b32 v0, v0, v1, 3 bitop3:0x6c
	v_lshlrev_b32_e32 v62, 3, v0
	v_bitop3_b32 v0, v1, v101, 2 bitop3:0x36
	s_lshl_b32 s10, s3, 7
	s_ashr_i32 s1, s0, 31
	v_lshlrev_b32_e32 v63, 3, v0
	v_add_u32_e32 v0, s10, v59
	s_lshl_b64 s[0:1], s[0:1], 14
	v_ashrrev_i32_e32 v1, 31, v0
	v_lshlrev_b64 v[0:1], s2, v[0:1]
	s_or_b32 s0, s0, s6
	v_lshl_add_u64 v[80:81], v[0:1], 0, s[0:1]
	v_mov_b64_e32 v[0:1], s[82:83]
	v_mad_u64_u32 v[0:1], s[6:7], v80, s86, v[0:1]
	s_and_b32 s4, s8, 0xffffff80
	v_mov_b32_e32 v2, v1
	s_ashr_i32 s5, s4, 31
	v_mad_u64_u32 v[2:3], s[6:7], v81, s86, v[2:3]
	s_lshl_b64 s[4:5], s[4:5], 1
	v_writelane_b32 v251, s8, 51
	s_ashr_i32 s8, s8, 7
	v_readlane_b32 s6, v253, 7
	s_add_u32 s6, s6, s4
	v_readlane_b32 s7, v253, 8
	v_mov_b32_e32 v1, v2
	s_addc_u32 s7, s7, s5
	s_lshl_b32 s11, 1, s2
	v_readlane_b32 s9, v253, 5
	v_lshl_add_u64 v[82:83], v[0:1], 0, s[4:5]
	s_add_u32 s4, s9, s4
	v_readlane_b32 s9, v253, 6
	s_addc_u32 s5, s9, s5
	s_add_i32 s8, s8, 1
	v_cvt_f32_i32_e32 v0, s8
	s_mov_b32 s12, 0x41400000
	v_ashrrev_i32_e32 v64, 4, v16
	v_add_u32_e32 v50, s10, v64
	v_mul_f32_e32 v17, 0xc1000000, v0
	v_div_scale_f32 v18, s[8:9], s12, s12, v17
	v_rcp_f32_e32 v19, v18
	s_mov_b32 s8, 0xc2fc0000
	s_waitcnt vmcnt(13)
	v_add_u32_e32 v24, 32, v50
	s_waitcnt vmcnt(11)
	v_add_u32_e32 v32, 64, v50
	v_fma_f32 v20, -v18, v19, 1.0
	v_fmac_f32_e32 v19, v20, v19
	v_div_scale_f32 v20, vcc, v17, s12, v17
	v_mul_f32_e32 v21, v20, v19
	v_fma_f32 v22, -v18, v21, v20
	v_fmac_f32_e32 v21, v22, v19
	v_fma_f32 v18, -v18, v21, v20
	v_div_fmas_f32 v18, v18, v19, v21
	v_div_fixup_f32 v17, v18, s12, v17
	v_cmp_gt_f32_e32 vcc, s8, v17
	s_and_b64 s[8:9], vcc, exec
	s_cselect_b32 s8, 0xffffffc0, 0
	v_cndmask_b32_e32 v18, 0, v236, vcc
	v_add_f32_e32 v17, v17, v18
	v_exp_f32_e32 v17, v17
	v_cvt_f32_u32_e32 v18, s11
	s_waitcnt vmcnt(9)
	v_add_u32_e32 v40, 0x60, v50
	v_and_b32_e32 v58, 15, v16
	v_lshlrev_b32_e32 v48, 4, v101
	v_mov_b32_e32 v49, v192
	v_ldexp_f32 v17, v17, s8
	v_ashrrev_i32_e32 v51, 31, v50
	v_ashrrev_i32_e32 v25, 31, v24
	v_ashrrev_i32_e32 v33, 31, v32
	v_ashrrev_i32_e32 v41, 31, v40
	v_lshl_add_u64 v[12:13], v[82:83], 0, v[48:49]
	v_mul_f32_e32 v49, v17, v18
	v_lshlrev_b32_e32 v52, 4, v58
	v_mov_b32_e32 v53, v192
	v_lshlrev_b64 v[16:17], s2, v[50:51]
	v_lshlrev_b64 v[24:25], s2, v[24:25]
	v_lshlrev_b64 v[32:33], s2, v[32:33]
	v_lshlrev_b64 v[40:41], s2, v[40:41]
	v_lshl_add_u64 v[54:55], s[6:7], 0, v[52:53]
	v_lshl_add_u64 v[56:57], s[4:5], 0, v[52:53]
	v_lshl_add_u64 v[16:17], v[16:17], 0, s[0:1]
	v_lshl_add_u64 v[24:25], v[24:25], 0, s[0:1]
	v_lshl_add_u64 v[32:33], v[32:33], 0, s[0:1]
	v_lshl_add_u64 v[40:41], v[40:41], 0, s[0:1]
	global_load_dwordx4 v[0:3], v[12:13], off
	global_load_dwordx4 v[4:7], v[12:13], off offset:64
	global_load_dwordx4 v[8:11], v[12:13], off offset:128
	s_nop 0
	global_load_dwordx4 v[12:15], v[12:13], off offset:192
	v_mad_u64_u32 v[18:19], s[4:5], v16, s86, v[54:55]
	v_mul_lo_u32 v17, v17, s86
	v_mad_u64_u32 v[20:21], s[4:5], v16, s86, v[56:57]
	v_mad_u64_u32 v[26:27], s[4:5], v24, s86, v[54:55]
	v_mul_lo_u32 v25, v25, s86
	v_mad_u64_u32 v[28:29], s[4:5], v24, s86, v[56:57]
	v_mad_u64_u32 v[34:35], s[4:5], v32, s86, v[54:55]
	v_mul_lo_u32 v33, v33, s86
	v_mad_u64_u32 v[36:37], s[4:5], v32, s86, v[56:57]
	v_mad_u64_u32 v[42:43], s[4:5], v40, s86, v[54:55]
	v_mul_lo_u32 v41, v41, s86
	s_waitcnt vmcnt(12)
; #define LAS __attribute__((address_space(3)))
; #define ATA_LOAD(c_) do { _Pragma("unroll") for (int it = 0; it < 4; ++it) { const size_t t_ = tok0 + (size_t)((n - 1 + (c_)) * 128 + srr + 32 * it) * d + r; \
;         kreg[it] = *(const u32x4*)(kbase + t_ * QKVW + sch * 8); vreg[it] = *(const u32x4*)(vbase + t_ * QKVW + sch * 8); } } while (0)
; __device__ __forceinline__ void attn_a_unit(LAS unsigned char* lds, bf16_t* QKV, float* LSE, int unit) {
;     ...
;     const int qi = wid * 16 + fr;
;     const LAS bf16_t* vsw[2] = {Vt + fr * VT_PITCH + 4 * (fq ^ (fr >> 3)), Vt + fr * VT_PITCH + 4 * (fq ^ (2 + (fr >> 3)))};
;     const size_t tq = tok0 + (size_t)(n * 128 + qi) * d + r;
;     bf16x8 qf[4];
; #pragma unroll
;     for (int ds = 0; ds < 4; ++ds) qf[ds] = *(const bf16x8*)(QKV + tq * QKVW + hh * 128 + ds * 32 + fq * 8);
;     f32x4 o[8];
; #pragma unroll
;     for (int i = 0; i < 8; ++i) o[i] = (f32x4){0.f, 0.f, 0.f, 0.f};
;     constexpr float LOG2E = 1.4426950408889634f;
;     const float sd2 = exp2f(-8.0f * (float)(hh + 1) / 12.0f) * (float)d * LOG2E;
;     const int dq = qi - 4 * fq;
;     float m_run = -1e30f, l_run = 0.f;
;     u32x4 kreg[4], vreg[4];
;     const int srr = tid >> 4, sch = tid & 15;
;     ...
;     ATA_LOAD(1);
;     const int cmin = (n > 0) ? 0 : 1;
	v_mad_u64_u32 v[44:45], s[4:5], v40, s86, v[56:57]
	v_add_u32_e32 v19, v17, v19
	v_add_u32_e32 v21, v17, v21
	v_add_u32_e32 v27, v25, v27
	v_add_u32_e32 v29, v25, v29
	v_add_u32_e32 v35, v33, v35
	v_add_u32_e32 v37, v33, v37
	v_add_u32_e32 v43, v41, v43
	v_add_u32_e32 v45, v41, v45
	global_load_dwordx4 v[16:19], v[18:19], off
	s_nop 0
	global_load_dwordx4 v[20:23], v[20:21], off
	s_nop 0
	global_load_dwordx4 v[24:27], v[26:27], off
	s_nop 0
	global_load_dwordx4 v[28:31], v[28:29], off
	s_nop 0
	global_load_dwordx4 v[32:35], v[34:35], off
	s_nop 0
	global_load_dwordx4 v[36:39], v[36:37], off
	s_nop 0
	global_load_dwordx4 v[40:43], v[42:43], off
	s_nop 0
	global_load_dwordx4 v[44:47], v[44:45], off
	s_cmp_eq_u32 s3, 0
	s_cselect_b64 s[4:5], -1, 0
	v_mul_f32_e32 v104, 0x3fb8aa3b, v49
	v_cndmask_b32_e64 v49, 0, 1, s[4:5]
	v_lshlrev_b32_e32 v102, 2, v101
	v_readfirstlane_b32 s76, v49
	v_add_u32_e32 v51, 0, v52
	v_lshlrev_b32_e32 v49, 2, v58
	v_and_b32_e32 v53, 64, v234
	v_mul_u32_u24_e32 v60, 0x110, v58
	v_mad_u32_u24 v61, v58, s85, 0
	v_sub_u32_e32 v105, v59, v102
	v_add_u32_e32 v52, 0, v48
	v_xor_b32_e32 v48, 16, v234
	v_add_u32_e32 v53, 64, v53
	v_xor_b32_e32 v59, v49, v64
	v_mad_u32_u24 v58, v58, s87, v51
	v_cmp_lt_i32_e32 vcc, v48, v53
	v_lshl_add_u32 v108, v59, 1, v58
	v_add_u32_e32 v59, 32, v64
	v_cndmask_b32_e32 v48, v234, v48, vcc
	v_xor_b32_e32 v59, v59, v49
	v_lshlrev_b32_e32 v106, 2, v48
	v_xor_b32_e32 v48, 32, v234
	v_lshl_add_u32 v109, v59, 1, v58
	v_add_u32_e32 v59, 64, v64
	v_cmp_lt_i32_e32 vcc, v48, v53
	v_xor_b32_e32 v59, v59, v49
	v_lshl_add_u32 v110, v59, 1, v58
	v_cndmask_b32_e32 v48, v234, v48, vcc
	v_add_u32_e32 v59, 0x60, v64
	v_lshlrev_b32_e32 v107, 2, v48
	v_add_u32_e32 v48, 0xffffff80, v50
	v_xor_b32_e32 v49, v59, v49
	v_lshl_add_u32 v111, v49, 1, v58
	v_ashrrev_i32_e32 v49, 31, v48
	v_lshlrev_b64 v[48:49], s2, v[48:49]
	v_lshl_add_u64 v[48:49], v[48:49], 0, s[0:1]
	v_mad_u64_u32 v[84:85], s[4:5], v48, s86, v[54:55]
	v_mul_lo_u32 v49, v49, s86
	v_mad_u64_u32 v[86:87], s[4:5], v48, s86, v[56:57]
	v_add_u32_e32 v48, 0xffffffa0, v50
	v_add_u32_e32 v85, v49, v85
	v_add_u32_e32 v87, v49, v87
	v_ashrrev_i32_e32 v49, 31, v48
	v_lshlrev_b64 v[48:49], s2, v[48:49]
	v_lshl_add_u64 v[48:49], v[48:49], 0, s[0:1]
	v_mad_u64_u32 v[88:89], s[4:5], v48, s86, v[54:55]
	v_mul_lo_u32 v49, v49, s86
	v_mad_u64_u32 v[90:91], s[4:5], v48, s86, v[56:57]
	v_subrev_u32_e32 v48, 64, v50
	v_add_u32_e32 v89, v49, v89
	v_add_u32_e32 v91, v49, v91
	v_ashrrev_i32_e32 v49, 31, v48
	v_lshlrev_b64 v[48:49], s2, v[48:49]
	v_lshl_add_u64 v[48:49], v[48:49], 0, s[0:1]
	v_mad_u64_u32 v[92:93], s[4:5], v48, s86, v[54:55]
	v_mul_lo_u32 v49, v49, s86
	v_mad_u64_u32 v[94:95], s[4:5], v48, s86, v[56:57]
	v_subrev_u32_e32 v48, 32, v50
	v_add_u32_e32 v93, v49, v93
	v_add_u32_e32 v95, v49, v95
	v_ashrrev_i32_e32 v49, 31, v48
	v_lshlrev_b64 v[48:49], s2, v[48:49]
	v_lshl_add_u64 v[48:49], v[48:49], 0, s[0:1]
	v_mad_u64_u32 v[96:97], s[0:1], v48, s86, v[54:55]
	v_mad_u64_u32 v[98:99], s[0:1], v48, s86, v[56:57]
	v_mov_b32_e32 v103, 0
	v_mul_lo_u32 v53, v64, s85
	v_mul_lo_u32 v49, v49, s86
	s_mov_b32 s33, 1
	v_add_u32_e32 v97, v49, v97
	v_add_u32_e32 v99, v49, v99
	v_mov_b32_e32 v100, 0xf149f2ca
	v_add_u32_e32 v112, v51, v53
	v_add_u32_e32 v113, v52, v60
	v_add_u32_e32 v114, v61, v62
	v_add_u32_e32 v115, v61, v63
	v_mov_b32_e32 v48, 0
	v_mov_b32_e32 v49, v103
	v_mov_b32_e32 v50, v103
	v_mov_b32_e32 v51, v103
	v_mov_b32_e32 v52, 0
	v_mov_b32_e32 v53, v103
	v_mov_b32_e32 v54, v103
	v_mov_b32_e32 v55, v103
	v_mov_b32_e32 v56, 0
	v_mov_b32_e32 v57, v103
	v_mov_b32_e32 v58, v103
	v_mov_b32_e32 v59, v103
	v_mov_b32_e32 v60, 0
	v_mov_b32_e32 v61, v103
	v_mov_b32_e32 v62, v103
	v_mov_b32_e32 v63, v103
	v_mov_b32_e32 v64, 0
	v_mov_b32_e32 v65, v103
	v_mov_b32_e32 v66, v103
	v_mov_b32_e32 v67, v103
	v_mov_b32_e32 v68, 0
	v_mov_b32_e32 v69, v103
	v_mov_b32_e32 v70, v103
	v_mov_b32_e32 v71, v103
	v_mov_b32_e32 v72, 0
	v_mov_b32_e32 v73, v103
	v_mov_b32_e32 v74, v103
	v_mov_b32_e32 v75, v103
	v_mov_b32_e32 v76, 0
	v_mov_b32_e32 v77, v103
	v_mov_b32_e32 v78, v103
	v_mov_b32_e32 v79, v103

; #define PG8_STAGE(bufoff, gbase, voff) do { _Pragma("unroll") for (int _i = 0; _i < 2; ++_i) \
;         __builtin_amdgcn_global_load_lds((const unsigned*)((const char*)(gbase) + (voff)[_i]), (LAS unsigned*)(lds + (bufoff) + ldsw + _i * 8192), 16, 0, 0); } while (0)
; #define PG8_LDA(dst, b, h) do { _Pragma("unroll") for (int m = 0; m < 4; ++m) _Pragma("unroll") for (int k = 0; k < 2; ++k) dst[m][k] = *(const LAS bf16x8*)(lds + PG8_SA(b, h) + aoff + m * 2048 + k * 1024); } while (0)
; #define PG8_LDB(dst, b, h) do { _Pragma("unroll") for (int n = 0; n < 2; ++n) _Pragma("unroll") for (int k = 0; k < 2; ++k) dst[n][k] = *(const LAS bf16x8*)(lds + PG8_SB(b, h) + boff + n * 2048 + k * 1024); } while (0)
; #define PG8_WAIT_V(n) asm volatile("s_waitcnt vmcnt(" #n ")" ::: "memory")
; #define PG8_WAIT_L(n) asm volatile("s_waitcnt lgkmcnt(" #n ")" ::: "memory")
; #define PG8_BAR __builtin_amdgcn_s_barrier()
; #define PG8_SCHED __builtin_amdgcn_sched_barrier(0)
; template <class Epi, bool PERMA = false, bool DUAL = false, bool ALIGN_EPI = true, bool SP2 = true>
; __device__ __forceinline__ void gemm_phase(LAS unsigned char* lds, const Gemm g, const StaticOrder& S, const Epi& E) {
;     ...
;         for (int t = 0; t < nt; t += 2) {
;             const bool last = (t == nt - 2);
;             const char* a1 = cA + (size_t)(t + 1) * kstep;
;             const char* a2 = last ? nA : cA + (size_t)(t + 2) * kstep; const char* b2 = last ? nB : cB + (size_t)(t + 2) * kstep;
;             const char* a3 = a2 + kstep; const char* b3 = b2 + kstep;
;             if constexpr (SP2) {
;             PG8_LDB(B0, 0, 0); PG8_LDB(B1, 0, 1); PG8_SCHED; PG8_LDA(At, 0, 0); PG8_STAGE(PG8_SA(1, 1), a1 + hstepA, voffA);
;             PG8_WAIT_V(8); PG8_WAIT_L(0); PG8_BAR; PG8_MMA(0, 0, At, B0); PG8_MMA(0, 1, At, B1); PG8_BAR; PG8_SCHED;
;             PG8_LDA(At, 0, 1); PG8_STAGE(PG8_SB(0, 0), b2, voffB); PG8_STAGE(PG8_SB(0, 1), b2 + hstepB, voffB); PG8_STAGE(PG8_SA(0, 0), a2, voffA);
;             PG8_WAIT_V(8); PG8_WAIT_L(0); PG8_BAR; PG8_MMA(1, 0, At, B0); PG8_MMA(1, 1, At, B1); PG8_BAR; PG8_SCHED;
;             PG8_LDB(B0, 1, 0); PG8_LDB(B1, 1, 1); PG8_SCHED; PG8_LDA(At, 1, 0); PG8_STAGE(PG8_SA(0, 1), a2 + hstepA, voffA);
;             PG8_WAIT_V(8); PG8_WAIT_L(0); PG8_BAR; PG8_MMA(0, 0, At, B0); PG8_MMA(0, 1, At, B1); PG8_BAR; PG8_SCHED;
.LBB0_528:
	s_add_u32 s22, s20, 0x100
	s_addc_u32 s23, s21, 0
	s_add_i32 s52, 0, 0x10000
	s_cmp_eq_u32 s51, 28
	s_cselect_b32 s27, s15, s23
	s_cselect_b32 s26, s39, s22
	s_cselect_b32 s25, s13, s50
	s_cselect_b32 s24, s48, s49
	s_add_i32 s53, 0, 0x14000
	v_add_u32_e32 v108, s52, v193
	v_add_u32_e32 v124, s53, v193
	ds_read_b128 v[96:99], v108
	ds_read_b128 v[100:103], v108 offset:1024
	ds_read_b128 v[104:107], v108 offset:2048
	ds_read_b128 v[108:111], v108 offset:3072
	ds_read_b128 v[112:115], v124
	ds_read_b128 v[116:119], v124 offset:1024
	ds_read_b128 v[120:123], v124 offset:2048
	ds_read_b128 v[124:127], v124 offset:3072
	v_lshl_add_u64 v[220:221], s[20:21], 0, v[216:217]
	s_add_i32 m0, s29, 0xc000
	ds_read_b128 v[128:131], v224
	ds_read_b128 v[132:135], v224 offset:1024
	ds_read_b128 v[136:139], v224 offset:2048
	ds_read_b128 v[144:147], v224 offset:3072
	ds_read_b128 v[152:155], v224 offset:4096
	ds_read_b128 v[160:163], v224 offset:5120
	ds_read_b128 v[168:171], v224 offset:6144
	ds_read_b128 v[188:191], v224 offset:7168
	global_load_lds_dwordx4 v[220:221], off
	v_lshl_add_u64 v[220:221], s[20:21], 0, v[218:219]
	s_add_i32 m0, s29, 0xe000
	s_nop 0
	global_load_lds_dwordx4 v[220:221], off
	s_waitcnt vmcnt(8)
	s_waitcnt lgkmcnt(0)
	s_barrier
	s_setprio 1
	s_waitcnt lgkmcnt(0)
	v_mfma_f32_16x16x32_bf16 v[184:187], v[96:99], v[128:131], v[184:187]
	v_mfma_f32_16x16x32_bf16 v[92:95], v[104:107], v[128:131], v[92:95]
	v_mfma_f32_16x16x32_bf16 v[180:183], v[96:99], v[136:139], v[180:183]
	v_mfma_f32_16x16x32_bf16 v[88:91], v[104:107], v[136:139], v[88:91]
	v_mfma_f32_16x16x32_bf16 v[176:179], v[96:99], v[152:155], v[176:179]
	v_mfma_f32_16x16x32_bf16 v[84:87], v[104:107], v[152:155], v[84:87]
	v_mfma_f32_16x16x32_bf16 v[172:175], v[96:99], v[168:171], v[172:175]
	v_mfma_f32_16x16x32_bf16 v[80:83], v[104:107], v[168:171], v[80:83]
	v_mfma_f32_16x16x32_bf16 v[184:187], v[100:103], v[132:135], v[184:187]
	v_mfma_f32_16x16x32_bf16 v[92:95], v[108:111], v[132:135], v[92:95]
	v_mfma_f32_16x16x32_bf16 v[180:183], v[100:103], v[144:147], v[180:183]
	v_mfma_f32_16x16x32_bf16 v[88:91], v[108:111], v[144:147], v[88:91]
	v_mfma_f32_16x16x32_bf16 v[176:179], v[100:103], v[160:163], v[176:179]
	v_mfma_f32_16x16x32_bf16 v[84:87], v[108:111], v[160:163], v[84:87]
	v_mfma_f32_16x16x32_bf16 v[172:175], v[100:103], v[188:191], v[172:175]
	v_mfma_f32_16x16x32_bf16 v[80:83], v[108:111], v[188:191], v[80:83]
	s_setprio 0
	s_setprio 1
	v_mfma_f32_16x16x32_bf16 v[164:167], v[112:115], v[128:131], v[164:167]
	v_mfma_f32_16x16x32_bf16 v[76:79], v[120:123], v[128:131], v[76:79]
	v_mfma_f32_16x16x32_bf16 v[72:75], v[120:123], v[136:139], v[72:75]
	v_mfma_f32_16x16x32_bf16 v[68:71], v[120:123], v[152:155], v[68:71]
	v_mfma_f32_16x16x32_bf16 v[64:67], v[120:123], v[168:171], v[64:67]
	v_mfma_f32_16x16x32_bf16 v[164:167], v[116:119], v[132:135], v[164:167]
	v_mfma_f32_16x16x32_bf16 v[76:79], v[124:127], v[132:135], v[76:79]
	v_mfma_f32_16x16x32_bf16 v[128:131], v[112:115], v[136:139], v[156:159]
	v_mfma_f32_16x16x32_bf16 v[72:75], v[124:127], v[144:147], v[72:75]
	v_mfma_f32_16x16x32_bf16 v[132:135], v[112:115], v[152:155], v[148:151]
	v_mfma_f32_16x16x32_bf16 v[68:71], v[124:127], v[160:163], v[68:71]
	v_mfma_f32_16x16x32_bf16 v[136:139], v[112:115], v[168:171], v[140:143]
	v_mfma_f32_16x16x32_bf16 v[64:67], v[124:127], v[188:191], v[64:67]
	v_mfma_f32_16x16x32_bf16 v[128:131], v[116:119], v[144:147], v[128:131]
	v_mfma_f32_16x16x32_bf16 v[132:135], v[116:119], v[160:163], v[132:135]
	v_mfma_f32_16x16x32_bf16 v[136:139], v[116:119], v[188:191], v[136:139]
	s_setprio 0
	s_barrier
	s_add_i32 s20, s52, s28
	v_lshl_add_u64 v[220:221], s[24:25], 0, v[210:211]
	s_mov_b32 m0, s20
	ds_read_b128 v[140:143], v224 offset:16384
	ds_read_b128 v[144:147], v224 offset:17408
	ds_read_b128 v[148:151], v224 offset:18432
	ds_read_b128 v[152:155], v224 offset:19456
	ds_read_b128 v[156:159], v224 offset:20480
	ds_read_b128 v[160:163], v224 offset:21504
	ds_read_b128 v[168:171], v224 offset:22528
	ds_read_b128 v[188:191], v224 offset:23552
	global_load_lds_dwordx4 v[220:221], off
	s_add_i32 m0, s20, 0x2000
	s_add_u32 s20, s24, 0x80000
	v_lshl_add_u64 v[238:239], s[24:25], 0, v[206:207]
	s_addc_u32 s21, s25, 0
	s_add_i32 s52, s53, s28
	global_load_lds_dwordx4 v[238:239], off
	v_lshl_add_u64 v[226:227], s[20:21], 0, v[210:211]
	s_mov_b32 m0, s52
	v_lshl_add_u64 v[240:241], s[26:27], 0, v[212:213]
	global_load_lds_dwordx4 v[226:227], off
	v_lshl_add_u64 v[226:227], s[20:21], 0, v[206:207]
	s_add_i32 m0, s52, 0x2000
	v_lshl_add_u64 v[242:243], s[26:27], 0, v[208:209]
	global_load_lds_dwordx4 v[226:227], off
	s_mov_b32 m0, s29
	s_nop 0
	global_load_lds_dwordx4 v[240:241], off
	s_mov_b32 m0, s30
	s_nop 0
	global_load_lds_dwordx4 v[242:243], off
	s_waitcnt vmcnt(8)
	s_waitcnt lgkmcnt(0)
	s_barrier
; #define PG8_STAGE(bufoff, gbase, voff) do { _Pragma("unroll") for (int _i = 0; _i < 2; ++_i) \
;         __builtin_amdgcn_global_load_lds((const unsigned*)((const char*)(gbase) + (voff)[_i]), (LAS unsigned*)(lds + (bufoff) + ldsw + _i * 8192), 16, 0, 0); } while (0)
; #define PG8_LDA(dst, b, h) do { _Pragma("unroll") for (int m = 0; m < 4; ++m) _Pragma("unroll") for (int k = 0; k < 2; ++k) dst[m][k] = *(const LAS bf16x8*)(lds + PG8_SA(b, h) + aoff + m * 2048 + k * 1024); } while (0)
; #define PG8_LDB(dst, b, h) do { _Pragma("unroll") for (int n = 0; n < 2; ++n) _Pragma("unroll") for (int k = 0; k < 2; ++k) dst[n][k] = *(const LAS bf16x8*)(lds + PG8_SB(b, h) + boff + n * 2048 + k * 1024); } while (0)
; #define PG8_MMA(ai, bj, At, Bt) do { __builtin_amdgcn_s_setprio(1); _Pragma("unroll") for (int m = 0; m < 4; ++m) _Pragma("unroll") for (int n = 0; n < 2; ++n) _Pragma("unroll") for (int k = 0; k < 2; ++k) \
;         acc[ai][bj][m][n] = __builtin_amdgcn_mfma_f32_16x16x32_bf16(Bt[n][k], At[m][k], acc[ai][bj][m][n], 0, 0, 0); __builtin_amdgcn_s_setprio(0); } while (0)
; #define PG8_BAR __builtin_amdgcn_s_barrier()
; template <class Epi, bool PERMA = false, bool DUAL = false, bool ALIGN_EPI = true, bool SP2 = true>
; __device__ __forceinline__ void gemm_phase(LAS unsigned char* lds, const Gemm g, const StaticOrder& S, const Epi& E) {
;     ...
;             PG8_LDB(B0, 0, 0); PG8_LDB(B1, 0, 1); PG8_SCHED; PG8_LDA(At, 0, 0); PG8_STAGE(PG8_SA(1, 1), a1 + hstepA, voffA);
;             PG8_WAIT_V(8); PG8_WAIT_L(0); PG8_BAR; PG8_MMA(0, 0, At, B0); PG8_MMA(0, 1, At, B1); PG8_BAR; PG8_SCHED;
;             PG8_LDA(At, 0, 1); PG8_STAGE(PG8_SB(0, 0), b2, voffB); PG8_STAGE(PG8_SB(0, 1), b2 + hstepB, voffB); PG8_STAGE(PG8_SA(0, 0), a2, voffA);
;             PG8_WAIT_V(8); PG8_WAIT_L(0); PG8_BAR; PG8_MMA(1, 0, At, B0); PG8_MMA(1, 1, At, B1); PG8_BAR; PG8_SCHED;
;             PG8_LDB(B0, 1, 0); PG8_LDB(B1, 1, 1); PG8_SCHED; PG8_LDA(At, 1, 0); PG8_STAGE(PG8_SA(0, 1), a2 + hstepA, voffA);
;             PG8_WAIT_V(8); PG8_WAIT_L(0); PG8_BAR; PG8_MMA(0, 0, At, B0); PG8_MMA(0, 1, At, B1); PG8_BAR; PG8_SCHED;
;             PG8_LDA(At, 1, 1); PG8_STAGE(PG8_SB(1, 0), b3, voffB); PG8_STAGE(PG8_SB(1, 1), b3 + hstepB, voffB); PG8_STAGE(PG8_SA(1, 0), a3, voffA);
;             PG8_WAIT_V(8); PG8_WAIT_L(0); PG8_BAR; PG8_MMA(1, 0, At, B0); PG8_MMA(1, 1, At, B1); PG8_BAR; PG8_SCHED;
	s_setprio 1
	s_waitcnt lgkmcnt(0)
	v_mfma_f32_16x16x32_bf16 v[60:63], v[96:99], v[140:143], v[60:63]
	v_mfma_f32_16x16x32_bf16 v[28:31], v[104:107], v[140:143], v[28:31]
	v_mfma_f32_16x16x32_bf16 v[56:59], v[96:99], v[148:151], v[56:59]
	v_mfma_f32_16x16x32_bf16 v[24:27], v[104:107], v[148:151], v[24:27]
	v_mfma_f32_16x16x32_bf16 v[52:55], v[96:99], v[156:159], v[52:55]
	v_mfma_f32_16x16x32_bf16 v[20:23], v[104:107], v[156:159], v[20:23]
	v_mfma_f32_16x16x32_bf16 v[48:51], v[96:99], v[168:171], v[48:51]
	v_mfma_f32_16x16x32_bf16 v[16:19], v[104:107], v[168:171], v[16:19]
	v_mfma_f32_16x16x32_bf16 v[60:63], v[100:103], v[144:147], v[60:63]
	v_mfma_f32_16x16x32_bf16 v[28:31], v[108:111], v[144:147], v[28:31]
	v_mfma_f32_16x16x32_bf16 v[56:59], v[100:103], v[152:155], v[56:59]
	v_mfma_f32_16x16x32_bf16 v[24:27], v[108:111], v[152:155], v[24:27]
	v_mfma_f32_16x16x32_bf16 v[52:55], v[100:103], v[160:163], v[52:55]
	v_mfma_f32_16x16x32_bf16 v[20:23], v[108:111], v[160:163], v[20:23]
	v_mfma_f32_16x16x32_bf16 v[48:51], v[100:103], v[188:191], v[48:51]
	v_mfma_f32_16x16x32_bf16 v[16:19], v[108:111], v[188:191], v[16:19]
	s_setprio 0
	s_setprio 1
	v_mfma_f32_16x16x32_bf16 v[44:47], v[112:115], v[140:143], v[44:47]
	v_mfma_f32_16x16x32_bf16 v[12:15], v[120:123], v[140:143], v[12:15]
	v_mfma_f32_16x16x32_bf16 v[40:43], v[112:115], v[148:151], v[40:43]
	v_mfma_f32_16x16x32_bf16 v[8:11], v[120:123], v[148:151], v[8:11]
	v_mfma_f32_16x16x32_bf16 v[36:39], v[112:115], v[156:159], v[36:39]
	v_mfma_f32_16x16x32_bf16 v[4:7], v[120:123], v[156:159], v[4:7]
	v_mfma_f32_16x16x32_bf16 v[32:35], v[112:115], v[168:171], v[32:35]
	v_mfma_f32_16x16x32_bf16 v[0:3], v[120:123], v[168:171], v[0:3]
	v_mfma_f32_16x16x32_bf16 v[44:47], v[116:119], v[144:147], v[44:47]
	v_mfma_f32_16x16x32_bf16 v[12:15], v[124:127], v[144:147], v[12:15]
	v_mfma_f32_16x16x32_bf16 v[40:43], v[116:119], v[152:155], v[40:43]
	v_mfma_f32_16x16x32_bf16 v[8:11], v[124:127], v[152:155], v[8:11]
	v_mfma_f32_16x16x32_bf16 v[36:39], v[116:119], v[160:163], v[36:39]
	v_mfma_f32_16x16x32_bf16 v[4:7], v[124:127], v[160:163], v[4:7]
	v_mfma_f32_16x16x32_bf16 v[32:35], v[116:119], v[188:191], v[32:35]
	v_mfma_f32_16x16x32_bf16 v[0:3], v[124:127], v[188:191], v[0:3]
	s_setprio 0
	s_barrier
	s_add_i32 s52, 0, 0x18000
	s_add_i32 s53, 0, 0x1c000
	v_add_u32_e32 v108, s52, v193
	v_add_u32_e32 v124, s53, v193
	ds_read_b128 v[96:99], v108
	ds_read_b128 v[100:103], v108 offset:1024
	ds_read_b128 v[104:107], v108 offset:2048
	ds_read_b128 v[108:111], v108 offset:3072
	ds_read_b128 v[112:115], v124
	ds_read_b128 v[116:119], v124 offset:1024
	ds_read_b128 v[120:123], v124 offset:2048
	ds_read_b128 v[124:127], v124 offset:3072
	s_add_u32 s20, s26, 0x80000
	s_addc_u32 s21, s27, 0
	s_mov_b32 m0, s31
	v_lshl_add_u64 v[156:157], s[20:21], 0, v[212:213]
	ds_read_b128 v[140:143], v224 offset:32768
	ds_read_b128 v[144:147], v224 offset:33792
	ds_read_b128 v[148:151], v224 offset:34816
	ds_read_b128 v[152:155], v224 offset:35840
	ds_read_b128 v[160:163], v224 offset:36864
	ds_read_b128 v[168:171], v224 offset:37888
	ds_read_b128 v[188:191], v224 offset:38912
	ds_read_b128 v[226:229], v224 offset:39936
	global_load_lds_dwordx4 v[156:157], off
	v_lshl_add_u64 v[156:157], s[20:21], 0, v[208:209]
	s_mov_b32 m0, s34
	s_nop 0
	global_load_lds_dwordx4 v[156:157], off
	s_waitcnt vmcnt(8)
	s_waitcnt lgkmcnt(0)
	s_barrier
	s_setprio 1
	s_waitcnt lgkmcnt(0)
	v_mfma_f32_16x16x32_bf16 v[156:159], v[96:99], v[140:143], v[184:187]
	v_mfma_f32_16x16x32_bf16 v[184:187], v[100:103], v[144:147], v[156:159]
	v_mfma_f32_16x16x32_bf16 v[156:159], v[96:99], v[148:151], v[180:183]
	v_mfma_f32_16x16x32_bf16 v[180:183], v[100:103], v[152:155], v[156:159]
	v_mfma_f32_16x16x32_bf16 v[156:159], v[96:99], v[160:163], v[176:179]
	v_mfma_f32_16x16x32_bf16 v[92:95], v[104:107], v[140:143], v[92:95]
	v_mfma_f32_16x16x32_bf16 v[88:91], v[104:107], v[148:151], v[88:91]
	v_mfma_f32_16x16x32_bf16 v[176:179], v[100:103], v[168:171], v[156:159]
	v_mfma_f32_16x16x32_bf16 v[84:87], v[104:107], v[160:163], v[84:87]
	v_mfma_f32_16x16x32_bf16 v[156:159], v[96:99], v[188:191], v[172:175]
	v_mfma_f32_16x16x32_bf16 v[80:83], v[104:107], v[188:191], v[80:83]
	v_mfma_f32_16x16x32_bf16 v[92:95], v[108:111], v[144:147], v[92:95]
	v_mfma_f32_16x16x32_bf16 v[88:91], v[108:111], v[152:155], v[88:91]
	v_mfma_f32_16x16x32_bf16 v[84:87], v[108:111], v[168:171], v[84:87]
	v_mfma_f32_16x16x32_bf16 v[172:175], v[100:103], v[226:229], v[156:159]
	v_mfma_f32_16x16x32_bf16 v[80:83], v[108:111], v[226:229], v[80:83]
	s_setprio 0
	s_setprio 1
	v_mfma_f32_16x16x32_bf16 v[156:159], v[112:115], v[140:143], v[164:167]
	v_mfma_f32_16x16x32_bf16 v[128:131], v[112:115], v[148:151], v[128:131]
	v_mfma_f32_16x16x32_bf16 v[164:167], v[116:119], v[144:147], v[156:159]
	v_mfma_f32_16x16x32_bf16 v[156:159], v[116:119], v[152:155], v[128:131]
	v_mfma_f32_16x16x32_bf16 v[128:131], v[112:115], v[160:163], v[132:135]
	v_mfma_f32_16x16x32_bf16 v[76:79], v[120:123], v[140:143], v[76:79]
	v_mfma_f32_16x16x32_bf16 v[72:75], v[120:123], v[148:151], v[72:75]
	v_mfma_f32_16x16x32_bf16 v[148:151], v[116:119], v[168:171], v[128:131]
	v_mfma_f32_16x16x32_bf16 v[68:71], v[120:123], v[160:163], v[68:71]
	v_mfma_f32_16x16x32_bf16 v[128:131], v[112:115], v[188:191], v[136:139]
	v_mfma_f32_16x16x32_bf16 v[64:67], v[120:123], v[188:191], v[64:67]
	v_mfma_f32_16x16x32_bf16 v[76:79], v[124:127], v[144:147], v[76:79]
	v_mfma_f32_16x16x32_bf16 v[72:75], v[124:127], v[152:155], v[72:75]
	v_mfma_f32_16x16x32_bf16 v[68:71], v[124:127], v[168:171], v[68:71]
	v_mfma_f32_16x16x32_bf16 v[140:143], v[116:119], v[226:229], v[128:131]
	v_mfma_f32_16x16x32_bf16 v[64:67], v[124:127], v[226:229], v[64:67]
	s_setprio 0
	s_barrier
; #define PG8_STAGE(bufoff, gbase, voff) do { _Pragma("unroll") for (int _i = 0; _i < 2; ++_i) \
;         __builtin_amdgcn_global_load_lds((const unsigned*)((const char*)(gbase) + (voff)[_i]), (LAS unsigned*)(lds + (bufoff) + ldsw + _i * 8192), 16, 0, 0); } while (0)
; #define PG8_LDA(dst, b, h) do { _Pragma("unroll") for (int m = 0; m < 4; ++m) _Pragma("unroll") for (int k = 0; k < 2; ++k) dst[m][k] = *(const LAS bf16x8*)(lds + PG8_SA(b, h) + aoff + m * 2048 + k * 1024); } while (0)
; #define PG8_LDB(dst, b, h) do { _Pragma("unroll") for (int n = 0; n < 2; ++n) _Pragma("unroll") for (int k = 0; k < 2; ++k) dst[n][k] = *(const LAS bf16x8*)(lds + PG8_SB(b, h) + boff + n * 2048 + k * 1024); } while (0)
; #define PG8_WAIT_V(n) asm volatile("s_waitcnt vmcnt(" #n ")" ::: "memory")
; template <class Epi, bool PERMA = false, bool DUAL = false, bool ALIGN_EPI = true, bool SP2 = true>
; __device__ __forceinline__ void gemm_phase(LAS unsigned char* lds, const Gemm g, const StaticOrder& S, const Epi& E) {
;     ...
;             PG8_WAIT_V(8); PG8_WAIT_L(0); PG8_BAR; PG8_MMA(1, 0, At, B0); PG8_MMA(1, 1, At, B1); PG8_BAR; PG8_SCHED;
;             PG8_LDB(B0, 1, 0); PG8_LDB(B1, 1, 1); PG8_SCHED; PG8_LDA(At, 1, 0); PG8_STAGE(PG8_SA(0, 1), a2 + hstepA, voffA);
;             PG8_WAIT_V(8); PG8_WAIT_L(0); PG8_BAR; PG8_MMA(0, 0, At, B0); PG8_MMA(0, 1, At, B1); PG8_BAR; PG8_SCHED;
;             PG8_LDA(At, 1, 1); PG8_STAGE(PG8_SB(1, 0), b3, voffB); PG8_STAGE(PG8_SB(1, 1), b3 + hstepB, voffB); PG8_STAGE(PG8_SA(1, 0), a3, voffA);
;             PG8_WAIT_V(8); PG8_WAIT_L(0); PG8_BAR; PG8_MMA(1, 0, At, B0); PG8_MMA(1, 1, At, B1); PG8_BAR; PG8_SCHED;
;     __device__ __forceinline__ void operator()(const f32x4 (&acc)[2][2][4][2], const Unit& u, int wr, int wc, int fr, int fq) const {
;     ...
;         const int ch0 = u.pn * HALF + wc * 32 + 8 * fq;
;         const int tok0 = u.pm * BM + wr * 64 + 4 * fr;
;         f32x4 wgt[2][8];
; #pragma unroll
;         for (int n = 0; n < 2; ++n) { const float* wp = cw + ch0 + 4 * n;
;             wgt[n][0] = *(const f32x4*)wp; wgt[n][1] = *(const f32x4*)(wp + 2 * DFF); wgt[n][2] = *(const f32x4*)(wp + 4 * DFF); wgt[n][3] = *(const f32x4*)(cb + ch0 + 4 * n);
;             wgt[n][4] = *(const f32x4*)(wp + DFF); wgt[n][5] = *(const f32x4*)(wp + 3 * DFF); wgt[n][6] = *(const f32x4*)(wp + 5 * DFF); wgt[n][7] = *(const f32x4*)(cb + DFF + ch0 + 4 * n); }
	s_add_i32 s20, s52, s28
	v_lshl_add_u64 v[220:221], v[220:221], 0, s[56:57]
	s_mov_b32 m0, s20
	ds_read_b128 v[128:131], v224 offset:49152
	ds_read_b128 v[132:135], v224 offset:50176
	ds_read_b128 v[136:139], v224 offset:51200
	ds_read_b128 v[144:147], v224 offset:52224
	ds_read_b128 v[152:155], v224 offset:53248
	ds_read_b128 v[160:163], v224 offset:54272
	ds_read_b128 v[168:171], v224 offset:55296
	ds_read_b128 v[188:191], v224 offset:56320
	global_load_lds_dwordx4 v[220:221], off
	s_add_i32 m0, s20, 0x2000
	s_add_u32 s20, s24, 0x80080
	v_lshl_add_u64 v[220:221], v[238:239], 0, s[56:57]
	s_addc_u32 s21, s25, 0
	s_add_i32 s24, s53, s28
	global_load_lds_dwordx4 v[220:221], off
	v_lshl_add_u64 v[220:221], s[20:21], 0, v[210:211]
	s_mov_b32 m0, s24
	s_nop 0
	global_load_lds_dwordx4 v[220:221], off
	v_lshl_add_u64 v[220:221], s[20:21], 0, v[206:207]
	s_add_i32 m0, s24, 0x2000
	s_nop 0
	global_load_lds_dwordx4 v[220:221], off
	v_lshl_add_u64 v[220:221], v[240:241], 0, s[56:57]
	s_mov_b32 m0, s35
	s_nop 0
	global_load_lds_dwordx4 v[220:221], off
	v_lshl_add_u64 v[220:221], v[242:243], 0, s[56:57]
	s_mov_b32 m0, s36
	s_nop 0
	global_load_lds_dwordx4 v[220:221], off
	s_waitcnt vmcnt(8)
	s_waitcnt lgkmcnt(0)
	s_barrier
	s_setprio 1
	s_waitcnt lgkmcnt(0)
	v_mfma_f32_16x16x32_bf16 v[60:63], v[96:99], v[128:131], v[60:63]
	v_mfma_f32_16x16x32_bf16 v[28:31], v[104:107], v[128:131], v[28:31]
	v_mfma_f32_16x16x32_bf16 v[56:59], v[96:99], v[136:139], v[56:59]
	v_mfma_f32_16x16x32_bf16 v[24:27], v[104:107], v[136:139], v[24:27]
	v_mfma_f32_16x16x32_bf16 v[52:55], v[96:99], v[152:155], v[52:55]
	v_mfma_f32_16x16x32_bf16 v[20:23], v[104:107], v[152:155], v[20:23]
	v_mfma_f32_16x16x32_bf16 v[48:51], v[96:99], v[168:171], v[48:51]
	v_mfma_f32_16x16x32_bf16 v[16:19], v[104:107], v[168:171], v[16:19]
	v_mfma_f32_16x16x32_bf16 v[60:63], v[100:103], v[132:135], v[60:63]
	v_mfma_f32_16x16x32_bf16 v[28:31], v[108:111], v[132:135], v[28:31]
	v_mfma_f32_16x16x32_bf16 v[56:59], v[100:103], v[144:147], v[56:59]
	v_mfma_f32_16x16x32_bf16 v[24:27], v[108:111], v[144:147], v[24:27]
	v_mfma_f32_16x16x32_bf16 v[52:55], v[100:103], v[160:163], v[52:55]
	v_mfma_f32_16x16x32_bf16 v[20:23], v[108:111], v[160:163], v[20:23]
	v_mfma_f32_16x16x32_bf16 v[48:51], v[100:103], v[188:191], v[48:51]
	v_mfma_f32_16x16x32_bf16 v[16:19], v[108:111], v[188:191], v[16:19]
	s_setprio 0
	s_setprio 1
	v_mfma_f32_16x16x32_bf16 v[44:47], v[112:115], v[128:131], v[44:47]
	v_mfma_f32_16x16x32_bf16 v[12:15], v[120:123], v[128:131], v[12:15]
	v_mfma_f32_16x16x32_bf16 v[40:43], v[112:115], v[136:139], v[40:43]
	v_mfma_f32_16x16x32_bf16 v[8:11], v[120:123], v[136:139], v[8:11]
	v_mfma_f32_16x16x32_bf16 v[36:39], v[112:115], v[152:155], v[36:39]
	v_mfma_f32_16x16x32_bf16 v[4:7], v[120:123], v[152:155], v[4:7]
	v_mfma_f32_16x16x32_bf16 v[32:35], v[112:115], v[168:171], v[32:35]
	v_mfma_f32_16x16x32_bf16 v[0:3], v[120:123], v[168:171], v[0:3]
	v_mfma_f32_16x16x32_bf16 v[44:47], v[116:119], v[132:135], v[44:47]
	v_mfma_f32_16x16x32_bf16 v[12:15], v[124:127], v[132:135], v[12:15]
	v_mfma_f32_16x16x32_bf16 v[40:43], v[116:119], v[144:147], v[40:43]
	v_mfma_f32_16x16x32_bf16 v[8:11], v[124:127], v[144:147], v[8:11]
	v_mfma_f32_16x16x32_bf16 v[36:39], v[116:119], v[160:163], v[36:39]
	v_mfma_f32_16x16x32_bf16 v[4:7], v[124:127], v[160:163], v[4:7]
	v_mfma_f32_16x16x32_bf16 v[32:35], v[116:119], v[188:191], v[32:35]
	v_mfma_f32_16x16x32_bf16 v[0:3], v[124:127], v[188:191], v[0:3]
	s_setprio 0
	s_barrier
	s_add_i32 s51, s51, 2
	s_add_u32 s49, s49, 0x100
	s_addc_u32 s50, s50, 0
	s_cmp_gt_u32 s51, 29
	s_mov_b64 s[20:21], s[22:23]
	s_cbranch_scc0 .LBB0_528
	v_lshl_or_b32 v220, s38, 7, v214
	v_ashrrev_i32_e32 v221, 31, v220
	v_lshlrev_b64 v[96:97], 2, v[220:221]
	v_lshl_add_u64 v[112:113], s[2:3], 0, v[96:97]
	v_add_co_u32_e32 v102, vcc, s72, v112
	s_mov_b64 s[20:21], 0xb000
	s_nop 0
	v_addc_co_u32_e32 v103, vcc, 0, v113, vcc
	s_mov_b32 s13, 0x16000
	v_lshl_add_u64 v[100:101], v[112:113], 0, s[20:21]
	s_mov_b64 s[20:21], 0x16000
	v_add_co_u32_e32 v106, vcc, s13, v112
	s_nop 0
	v_lshl_add_u64 v[104:105], v[112:113], 0, s[20:21]
	v_addc_co_u32_e32 v107, vcc, 0, v113, vcc
	v_lshl_add_u64 v[114:115], s[6:7], 0, v[96:97]
	v_lshl_add_u64 v[188:189], s[10:11], 0, v[96:97]
	global_load_dwordx4 v[96:99], v[112:113], off offset:16
	global_load_dwordx4 v[128:131], v[112:113], off
	global_load_dwordx4 v[132:135], v[102:103], off
	s_nop 0
	global_load_dwordx4 v[100:103], v[100:101], off offset:16
	s_nop 0
	global_load_dwordx4 v[136:139], v[106:107], off
	s_nop 0
	global_load_dwordx4 v[104:107], v[104:105], off offset:16
	s_nop 0
	global_load_dwordx4 v[108:111], v[114:115], off offset:16
	global_load_dwordx4 v[144:147], v[114:115], off
	s_movk_i32 s13, 0x5000
	v_add_co_u32_e32 v116, vcc, s13, v112
	s_mov_b64 s[20:21], 0x5800
	s_nop 0
	v_addc_co_u32_e32 v117, vcc, 0, v113, vcc
	s_mov_b32 s13, 0x10000
	v_lshl_add_u64 v[114:115], v[112:113], 0, s[20:21]
	s_mov_b64 s[20:21], 0x10800
	v_add_co_u32_e32 v120, vcc, s13, v112
	global_load_dwordx4 v[160:163], v[116:117], off offset:2048
	s_nop 0
	global_load_dwordx4 v[116:119], v[114:115], off offset:16
	v_lshl_add_u64 v[114:115], v[112:113], 0, s[20:21]
	v_addc_co_u32_e32 v121, vcc, 0, v113, vcc
	s_mov_b64 s[20:21], 0x1b800
	s_mov_b32 s13, 0x1b000
	global_load_dwordx4 v[168:171], v[120:121], off offset:2048
	s_nop 0
	global_load_dwordx4 v[120:123], v[114:115], off offset:16
	v_lshl_add_u64 v[114:115], v[112:113], 0, s[20:21]
	v_add_co_u32_e32 v112, vcc, s13, v112
	s_nop 0
	v_addc_co_u32_e32 v113, vcc, 0, v113, vcc
	global_load_dwordx4 v[152:155], v[112:113], off offset:2048
	s_nop 0
	global_load_dwordx4 v[112:115], v[114:115], off offset:16
	s_nop 0
	global_load_dwordx4 v[124:127], v[188:189], off offset:16
	s_nop 0
	global_load_dwordx4 v[188:191], v[188:189], off
	s_and_b64 vcc, exec, s[4:5]
	s_cbranch_vccz .LBB0_531
	s_barrier
; #define LAS __attribute__((address_space(3)))
;     __device__ __forceinline__ void operator()(const f32x4 (&acc)[2][2][4][2], const Unit& u, int wr, int wc, int fr, int fq) const {
;         LAS float* X = (LAS float*)xch;
;         if (fr == 15) {
; #pragma unroll
;             for (int ai = 0; ai < 2; ++ai) { LAS float* sl = X + ((ai * 2 + wr) * 4 + wc) * 128 + fq;
; #pragma unroll
;                 for (int bj = 0; bj < 2; ++bj)
; #pragma unroll
;                     for (int n = 0; n < 2; ++n)
; #pragma unroll
;                         for (int j = 0; j < 4; ++j) { const int v = ((bj * 2 + n) * 4 + j) * 2; sl[v * 4] = acc[ai][bj][2][n][j]; sl[(v + 1) * 4] = acc[ai][bj][3][n][j]; } }
;         }
;         { const int colb = wc * 32 + 8 * fq;
;           if (wr == 0 && fr == 0) { float* tp = TOP + ((size_t)u.pm * 2) * (2 * DFF) + u.pn * BM + colb;
; #pragma unroll
;               for (int bj = 0; bj < 2; ++bj)
; #pragma unroll
;                   for (int n = 0; n < 2; ++n) { *(f32x4*)(tp + bj * HALF + 4 * n) = acc[0][bj][0][n]; *(f32x4*)(tp + (2 * DFF) + bj * HALF + 4 * n) = acc[0][bj][1][n]; } }
;           if (wr == 1 && fr == 15) { float* bp = BOT + ((size_t)u.pm * 2) * (2 * DFF) + u.pn * BM + colb;
; #pragma unroll
;               for (int bj = 0; bj < 2; ++bj)
; #pragma unroll
;                   for (int n = 0; n < 2; ++n) { *(f32x4*)(bp + bj * HALF + 4 * n) = acc[1][bj][2][n]; *(f32x4*)(bp + (2 * DFF) + bj * HALF + 4 * n) = acc[1][bj][3][n]; } } }
;         asm volatile("s_waitcnt lgkmcnt(0)" ::: "memory");
;         __builtin_amdgcn_s_barrier();
;         asm volatile("" ::: "memory");
;     ...
;                     const float hg2a = hl[vga * 4], hg1a = hl[(vga + 1) * 4], hg2b = hl[vgb * 4], hg1b = hl[(vgb + 1) * 4];
;                     const float hv2a = hl[vva * 4], hv1a = hl[(vva + 1) * 4], hv2b = hl[vvb * 4], hv1b = hl[(vvb + 1) * 4];
;     ...
;                     const f32x2 g0 = UC_PAIR(0, 0), g1 = UC_PAIR(0, 1), g2 = UC_PAIR(0, 2), g3 = UC_PAIR(0, 3);
;                     const f32x2 v0 = UC_PAIR(1, 0), v1 = UC_PAIR(1, 1), v2 = UC_PAIR(1, 2), v3 = UC_PAIR(1, 3);
;     ...
;                     f32x2 gp1, gp2, vp1, vp2;
;                     gp1.x = dpp_shr1_keep(hg1a, g3.x); gp1.y = dpp_shr1_keep(hg1b, g3.y); gp2.x = dpp_shr1_keep(hg2a, g2.x); gp2.y = dpp_shr1_keep(hg2b, g2.y);
.LBB0_531:
	s_and_saveexec_b64 s[20:21], s[40:41]
	s_cbranch_execz .LBB0_533
	v_add_u32_e32 v246, 0x1000, v222
	ds_write2_b32 v222, v176, v172 offset1:4
	ds_write2_b32 v222, v177, v173 offset0:8 offset1:12
	ds_write2_b32 v222, v178, v174 offset0:16 offset1:20
	ds_write2_b32 v222, v179, v175 offset0:24 offset1:28
	ds_write2_b32 v222, v84, v80 offset0:32 offset1:36
	ds_write2_b32 v222, v85, v81 offset0:40 offset1:44
	ds_write2_b32 v222, v86, v82 offset0:48 offset1:52
	ds_write2_b32 v222, v87, v83 offset0:56 offset1:60
	ds_write2_b32 v222, v148, v140 offset0:64 offset1:68
	ds_write2_b32 v222, v149, v141 offset0:72 offset1:76
	ds_write2_b32 v222, v150, v142 offset0:80 offset1:84
	ds_write2_b32 v222, v151, v143 offset0:88 offset1:92
	ds_write2_b32 v222, v68, v64 offset0:96 offset1:100
	ds_write2_b32 v222, v69, v65 offset0:104 offset1:108
	ds_write2_b32 v222, v70, v66 offset0:112 offset1:116
	ds_write2_b32 v222, v71, v67 offset0:120 offset1:124
	ds_write2_b32 v246, v52, v48 offset1:4
	ds_write2_b32 v246, v53, v49 offset0:8 offset1:12
	ds_write2_b32 v246, v54, v50 offset0:16 offset1:20
	ds_write2_b32 v246, v55, v51 offset0:24 offset1:28
	ds_write2_b32 v246, v20, v16 offset0:32 offset1:36
	ds_write2_b32 v246, v21, v17 offset0:40 offset1:44
	ds_write2_b32 v246, v22, v18 offset0:48 offset1:52
	ds_write2_b32 v246, v23, v19 offset0:56 offset1:60
	ds_write2_b32 v246, v36, v32 offset0:64 offset1:68
	ds_write2_b32 v246, v37, v33 offset0:72 offset1:76
	ds_write2_b32 v246, v38, v34 offset0:80 offset1:84
	ds_write2_b32 v246, v39, v35 offset0:88 offset1:92
	ds_write2_b32 v246, v4, v0 offset0:96 offset1:100
	ds_write2_b32 v246, v5, v1 offset0:104 offset1:108
	ds_write2_b32 v246, v6, v2 offset0:112 offset1:116
	ds_write2_b32 v246, v7, v3 offset0:120 offset1:124
.LBB0_533:
	s_or_b64 exec, exec, s[20:21]
	s_mul_hi_i32 s13, s33, 0x16000
	s_mul_i32 s15, s33, 0x16000
	v_lshlrev_b32_e32 v246, 2, v214
	s_and_saveexec_b64 s[20:21], s[42:43]
	s_cbranch_execz .LBB0_535
	v_readlane_b32 s22, v253, 11
	v_readlane_b32 s23, v253, 12
	s_add_u32 s24, s22, s15
	s_addc_u32 s25, s23, s13
	s_lshl_b32 s22, s38, 8
	s_ashr_i32 s23, s22, 31
	s_lshl_b64 s[22:23], s[22:23], 2
	s_add_u32 s22, s24, s22
	s_addc_u32 s23, s25, s23
	v_mov_b32_e32 v247, v192
	v_lshl_add_u64 v[248:249], s[22:23], 0, v[246:247]
	v_add_co_u32_e32 v248, vcc, 0xb000, v248
	global_store_dwordx4 v246, v[184:187], s[22:23]
	s_nop 0
	v_addc_co_u32_e32 v249, vcc, 0, v249, vcc
	global_store_dwordx4 v[248:249], v[180:183], off
	global_store_dwordx4 v246, v[92:95], s[22:23] offset:16
	global_store_dwordx4 v[248:249], v[88:91], off offset:16
	global_store_dwordx4 v246, v[164:167], s[22:23] offset:512
	global_store_dwordx4 v[248:249], v[156:159], off offset:512
	global_store_dwordx4 v246, v[76:79], s[22:23] offset:528
	global_store_dwordx4 v[248:249], v[72:75], off offset:528
.LBB0_535:
	s_or_b64 exec, exec, s[20:21]
	s_and_saveexec_b64 s[20:21], s[8:9]
	s_cbranch_execz .LBB0_537
	v_readlane_b32 s22, v253, 13
	v_readlane_b32 s23, v253, 14
	s_add_u32 s15, s22, s15
	s_addc_u32 s13, s23, s13
	s_lshl_b32 s22, s38, 8
	s_ashr_i32 s23, s22, 31
	s_lshl_b64 s[22:23], s[22:23], 2
	s_add_u32 s22, s15, s22
	s_addc_u32 s23, s13, s23
	v_mov_b32_e32 v247, v192
	v_lshl_add_u64 v[248:249], s[22:23], 0, v[246:247]
	v_add_co_u32_e32 v248, vcc, 0xb000, v248
	global_store_dwordx4 v246, v[52:55], s[22:23]
	s_nop 0
	v_addc_co_u32_e32 v249, vcc, 0, v249, vcc
	global_store_dwordx4 v[248:249], v[48:51], off
	global_store_dwordx4 v246, v[20:23], s[22:23] offset:16
	global_store_dwordx4 v[248:249], v[16:19], off offset:16
	global_store_dwordx4 v246, v[36:39], s[22:23] offset:512
	global_store_dwordx4 v[248:249], v[32:35], off offset:512
	global_store_dwordx4 v246, v[4:7], s[22:23] offset:528
	global_store_dwordx4 v[248:249], v[0:3], off offset:528
.LBB0_537:
	s_or_b64 exec, exec, s[20:21]
	s_waitcnt lgkmcnt(0)
	s_barrier
	s_mov_b32 s21, 0
	s_mov_b32 s20, 0x40135761
	ds_read2_b32 v[228:229], v223 offset1:4
	ds_read2_b32 v[238:239], v223 offset0:8 offset1:12
	ds_read2_b32 v[240:241], v223 offset0:64 offset1:68
	ds_read2_b32 v[242:243], v223 offset0:72 offset1:76
	v_lshl_add_u32 v226, s33, 8, v215
	s_waitcnt lgkmcnt(0)
	v_mov_b32_dpp v229, v172 row_shr:1 row_mask:0xf bank_mask:0xf
	v_mov_b32_dpp v238, v177 row_shr:1 row_mask:0xf bank_mask:0xf
	v_mov_b32_dpp v239, v173 row_shr:1 row_mask:0xf bank_mask:0xf
	v_mov_b32_e32 v244, v229
	v_mov_b32_dpp v228, v176 row_shr:1 row_mask:0xf bank_mask:0xf
	v_mov_b32_e32 v229, v238
	v_mov_b32_e32 v245, v239
	v_mov_b32_dpp v241, v140 row_shr:1 row_mask:0xf bank_mask:0xf
	v_mov_b32_dpp v243, v141 row_shr:1 row_mask:0xf bank_mask:0xf
	v_mov_b32_dpp v242, v149 row_shr:1 row_mask:0xf bank_mask:0xf
	v_mov_b32_e32 v238, v241
	v_mov_b32_e32 v239, v243
	v_mov_b32_e32 v241, v242
	v_mov_b32_dpp v240, v148 row_shr:1 row_mask:0xf bank_mask:0xf
	s_waitcnt vmcnt(0)
; __device__ __forceinline__ f32x2 lo2(const f32x4 v) { return __builtin_shufflevector(v, v, 0, 1); }
;     __device__ __forceinline__ void operator()(const f32x4 (&acc)[2][2][4][2], const Unit& u, int wr, int wc, int fr, int fq) const {
;     ...
;                 for (int jp = 0; jp < 2; ++jp) {
;                     const int ja = 2 * jp, jb = 2 * jp + 1;
;                     const int vga = ((0 * 2 + n) * 4 + ja) * 2, vgb = ((0 * 2 + n) * 4 + jb) * 2, vva = ((1 * 2 + n) * 4 + ja) * 2, vvb = ((1 * 2 + n) * 4 + jb) * 2;
;                     const float hg2a = hl[vga * 4], hg1a = hl[(vga + 1) * 4], hg2b = hl[vgb * 4], hg1b = hl[(vgb + 1) * 4];
;                     const float hv2a = hl[vva * 4], hv1a = hl[(vva + 1) * 4], hv2b = hl[vvb * 4], hv1b = hl[(vvb + 1) * 4];
;     ...
;                     const f32x2 g0 = UC_PAIR(0, 0), g1 = UC_PAIR(0, 1), g2 = UC_PAIR(0, 2), g3 = UC_PAIR(0, 3);
;                     const f32x2 v0 = UC_PAIR(1, 0), v1 = UC_PAIR(1, 1), v2 = UC_PAIR(1, 2), v3 = UC_PAIR(1, 3);
;     ...
;                     f32x2 gp1, gp2, vp1, vp2;
;                     gp1.x = dpp_shr1_keep(hg1a, g3.x); gp1.y = dpp_shr1_keep(hg1b, g3.y); gp2.x = dpp_shr1_keep(hg2a, g2.x); gp2.y = dpp_shr1_keep(hg2b, g2.y);
;                     vp1.x = dpp_shr1_keep(hv1a, v3.x); vp1.y = dpp_shr1_keep(hv1b, v3.y); vp2.x = dpp_shr1_keep(hv2a, v2.x); vp2.y = dpp_shr1_keep(hv2b, v2.y);
;                     const f32x2 a0 = jp == 0 ? lo2(wg0) : hi2(wg0), a1 = jp == 0 ? lo2(wg1) : hi2(wg1), a2 = jp == 0 ? lo2(wg2) : hi2(wg2), ab = jp == 0 ? lo2(bg) : hi2(bg);
;                     const f32x2 c0 = jp == 0 ? lo2(wv0) : hi2(wv0), c1 = jp == 0 ? lo2(wv1) : hi2(wv1), c2 = jp == 0 ? lo2(wv2) : hi2(wv2), cb_ = jp == 0 ? lo2(bv) : hi2(bv);
;                     const f32x2 yg0 = ab + a0 * gp2 + a1 * gp1 + a2 * g0, yv0 = cb_ + c0 * vp2 + c1 * vp1 + c2 * v0;
;                     const f32x2 yg1 = ab + a0 * gp1 + a1 * g0 + a2 * g1, yv1 = cb_ + c0 * vp1 + c1 * v0 + c2 * v1;
;                     const f32x2 yg2 = ab + a0 * g0 + a1 * g1 + a2 * g2, yv2 = cb_ + c0 * v0 + c1 * v1 + c2 * v2;
;                     const f32x2 yg3 = ab + a0 * g1 + a1 * g2 + a2 * g3, yv3 = cb_ + c0 * v1 + c1 * v2 + c2 * v3;
;                     const f32x2 r0 = gelu_tanh_fast2(yg0) * yv0, r1 = gelu_tanh_fast2(yg1) * yv1, r2 = gelu_tanh_fast2(yg2) * yv2, r3 = gelu_tanh_fast2(yg3) * yv3;
	v_pk_fma_f32 v[228:229], v[128:129], v[228:229], v[144:145]
	s_nop 0
	v_pk_fma_f32 v[228:229], v[132:133], v[244:245], v[228:229]
	v_pk_fma_f32 v[242:243], v[128:129], v[244:245], v[144:145]
	v_pk_fma_f32 v[228:229], v[184:185], v[136:137], v[228:229]
	v_pk_fma_f32 v[242:243], v[184:185], v[132:133], v[242:243]
	v_pk_fma_f32 v[184:185], v[184:185], v[128:129], v[144:145]
	v_pk_fma_f32 v[242:243], v[180:181], v[136:137], v[242:243]
	v_pk_fma_f32 v[184:185], v[180:181], v[132:133], v[184:185]
	v_pk_fma_f32 v[180:181], v[180:181], v[128:129], v[144:145]
	v_pk_fma_f32 v[184:185], v[176:177], v[136:137], v[184:185]
	v_pk_fma_f32 v[176:177], v[176:177], v[132:133], v[180:181]
	v_pk_mul_f32 v[180:181], v[184:185], v[184:185]
	v_pk_fma_f32 v[176:177], v[172:173], v[136:137], v[176:177]
	v_mov_b64_e32 v[172:173], s[20:21]
	s_mov_b32 s20, 0x3dd2d3e7
	v_pk_fma_f32 v[180:181], v[180:181], s[20:21], v[172:173] op_sel_hi:[1,0,0]
	v_pk_fma_f32 v[240:241], v[160:161], v[240:241], v[188:189]
	v_pk_mul_f32 v[180:181], v[184:185], v[180:181]
	v_pk_fma_f32 v[240:241], v[168:169], v[238:239], v[240:241]
	v_exp_f32_e32 v180, v180
	v_exp_f32_e32 v181, v181
	v_pk_fma_f32 v[238:239], v[160:161], v[238:239], v[188:189]
	v_pk_fma_f32 v[240:241], v[164:165], v[152:153], v[240:241]
	v_pk_fma_f32 v[238:239], v[164:165], v[168:169], v[238:239]
	v_pk_add_f32 v[180:181], v[180:181], 1.0 op_sel_hi:[1,0]
	v_pk_fma_f32 v[164:165], v[164:165], v[160:161], v[188:189]
	v_rcp_f32_e32 v180, v180
	v_rcp_f32_e32 v181, v181
	v_pk_fma_f32 v[238:239], v[156:157], v[152:153], v[238:239]
	v_pk_fma_f32 v[164:165], v[156:157], v[168:169], v[164:165]
	v_pk_fma_f32 v[156:157], v[156:157], v[160:161], v[188:189]
	v_pk_fma_f32 v[164:165], v[148:149], v[152:153], v[164:165]
	v_pk_fma_f32 v[148:149], v[148:149], v[168:169], v[156:157]
	v_pk_fma_f32 v[180:181], v[184:185], v[180:181], v[184:185] neg_lo:[1,0,0] neg_hi:[1,0,0]
	v_pk_fma_f32 v[140:141], v[140:141], v[152:153], v[148:149]
	v_pk_mul_f32 v[148:149], v[228:229], v[228:229]
	v_pk_mul_f32 v[180:181], v[164:165], v[180:181]
	v_pk_fma_f32 v[148:149], v[148:149], s[20:21], v[172:173] op_sel_hi:[1,0,0]
	v_pk_mul_f32 v[164:165], v[176:177], v[176:177]
	v_pk_mul_f32 v[148:149], v[228:229], v[148:149]
	v_pk_fma_f32 v[164:165], v[164:165], s[20:21], v[172:173] op_sel_hi:[1,0,0]
	v_exp_f32_e32 v148, v148
	v_exp_f32_e32 v149, v149
	v_pk_mul_f32 v[164:165], v[176:177], v[164:165]
	v_pk_mul_f32 v[156:157], v[242:243], v[242:243]
	v_exp_f32_e32 v164, v164
	v_exp_f32_e32 v165, v165
	v_pk_add_f32 v[148:149], v[148:149], 1.0 op_sel_hi:[1,0]
	v_pk_fma_f32 v[156:157], v[156:157], s[20:21], v[172:173] op_sel_hi:[1,0,0]
	v_rcp_f32_e32 v148, v148
	v_rcp_f32_e32 v149, v149
	v_pk_add_f32 v[164:165], v[164:165], 1.0 op_sel_hi:[1,0]
	v_pk_mul_f32 v[156:157], v[242:243], v[156:157]
	v_rcp_f32_e32 v164, v164
	v_rcp_f32_e32 v165, v165
	v_exp_f32_e32 v156, v156
	v_exp_f32_e32 v157, v157
	v_pk_fma_f32 v[148:149], v[228:229], v[148:149], v[228:229] neg_lo:[1,0,0] neg_hi:[1,0,0]
	v_pk_fma_f32 v[164:165], v[176:177], v[164:165], v[176:177] neg_lo:[1,0,0] neg_hi:[1,0,0]
	v_pk_mul_f32 v[148:149], v[240:241], v[148:149]
	v_pk_add_f32 v[156:157], v[156:157], 1.0 op_sel_hi:[1,0]
	v_pk_mul_f32 v[140:141], v[140:141], v[164:165]
	v_cvt_pk_bf16_f32 v164, v148, v149
	v_cvt_pk_bf16_f32 v148, v180, v181
	ds_read2_b32 v[176:177], v223 offset0:16 offset1:20
	ds_read2_b32 v[180:181], v223 offset0:24 offset1:28
	ds_read2_b32 v[184:185], v223 offset0:80 offset1:84
	ds_read2_b32 v[228:229], v223 offset0:88 offset1:92
	v_rcp_f32_e32 v156, v156
	v_rcp_f32_e32 v157, v157
	s_waitcnt lgkmcnt(3)
	v_mov_b32_dpp v177, v174 row_shr:1 row_mask:0xf bank_mask:0xf
	s_waitcnt lgkmcnt(2)
	v_mov_b32_dpp v180, v179 row_shr:1 row_mask:0xf bank_mask:0xf
	s_waitcnt lgkmcnt(1)
	v_mov_b32_dpp v185, v142 row_shr:1 row_mask:0xf bank_mask:0xf
	v_pk_fma_f32 v[156:157], v[242:243], v[156:157], v[242:243] neg_lo:[1,0,0] neg_hi:[1,0,0]
	s_waitcnt lgkmcnt(0)
	v_mov_b32_dpp v228, v151 row_shr:1 row_mask:0xf bank_mask:0xf
	v_pk_mul_f32 v[156:157], v[238:239], v[156:157]
	v_mov_b32_dpp v181, v175 row_shr:1 row_mask:0xf bank_mask:0xf
	v_mov_b32_e32 v238, v177
	v_mov_b32_e32 v177, v180
	v_mov_b32_dpp v229, v143 row_shr:1 row_mask:0xf bank_mask:0xf
	v_mov_b32_e32 v180, v185
	v_mov_b32_dpp v184, v150 row_shr:1 row_mask:0xf bank_mask:0xf
	v_mov_b32_e32 v185, v228
	v_mov_b32_e32 v239, v181
	v_mov_b32_e32 v181, v229
	v_pk_fma_f32 v[184:185], v[162:163], v[184:185], v[190:191]
	v_mov_b32_dpp v176, v178 row_shr:1 row_mask:0xf bank_mask:0xf
	v_pk_fma_f32 v[184:185], v[170:171], v[180:181], v[184:185]
	v_pk_fma_f32 v[180:181], v[162:163], v[180:181], v[190:191]
	v_pk_fma_f32 v[176:177], v[130:131], v[176:177], v[146:147]
	v_pk_fma_f32 v[184:185], v[166:167], v[154:155], v[184:185]
	v_pk_fma_f32 v[180:181], v[166:167], v[170:171], v[180:181]
	v_pk_fma_f32 v[166:167], v[166:167], v[162:163], v[190:191]
	v_pk_fma_f32 v[176:177], v[134:135], v[238:239], v[176:177]
	v_pk_fma_f32 v[180:181], v[158:159], v[154:155], v[180:181]
	v_pk_fma_f32 v[166:167], v[158:159], v[170:171], v[166:167]
	v_pk_fma_f32 v[158:159], v[158:159], v[162:163], v[190:191]
	v_pk_fma_f32 v[176:177], v[186:187], v[138:139], v[176:177]
	v_pk_fma_f32 v[166:167], v[150:151], v[154:155], v[166:167]
	v_pk_fma_f32 v[150:151], v[150:151], v[170:171], v[158:159]
	v_pk_fma_f32 v[228:229], v[130:131], v[238:239], v[146:147]
	v_pk_fma_f32 v[142:143], v[142:143], v[154:155], v[150:151]
	v_pk_mul_f32 v[150:151], v[176:177], v[176:177]
	v_pk_fma_f32 v[228:229], v[186:187], v[134:135], v[228:229]
	v_pk_fma_f32 v[150:151], v[150:151], s[20:21], v[172:173] op_sel_hi:[1,0,0]
; __device__ __forceinline__ f32x2 lo2(const f32x4 v) { return __builtin_shufflevector(v, v, 0, 1); }
;     __device__ __forceinline__ void operator()(const f32x4 (&acc)[2][2][4][2], const Unit& u, int wr, int wc, int fr, int fq) const {
;     ...
;                 for (int jp = 0; jp < 2; ++jp) {
;                     const int ja = 2 * jp, jb = 2 * jp + 1;
;                     const int vga = ((0 * 2 + n) * 4 + ja) * 2, vgb = ((0 * 2 + n) * 4 + jb) * 2, vva = ((1 * 2 + n) * 4 + ja) * 2, vvb = ((1 * 2 + n) * 4 + jb) * 2;
;                     const float hg2a = hl[vga * 4], hg1a = hl[(vga + 1) * 4], hg2b = hl[vgb * 4], hg1b = hl[(vgb + 1) * 4];
;                     const float hv2a = hl[vva * 4], hv1a = hl[(vva + 1) * 4], hv2b = hl[vvb * 4], hv1b = hl[(vvb + 1) * 4];
;     ...
;                     const f32x2 g0 = UC_PAIR(0, 0), g1 = UC_PAIR(0, 1), g2 = UC_PAIR(0, 2), g3 = UC_PAIR(0, 3);
;                     const f32x2 v0 = UC_PAIR(1, 0), v1 = UC_PAIR(1, 1), v2 = UC_PAIR(1, 2), v3 = UC_PAIR(1, 3);
;     ...
;                     f32x2 gp1, gp2, vp1, vp2;
;                     gp1.x = dpp_shr1_keep(hg1a, g3.x); gp1.y = dpp_shr1_keep(hg1b, g3.y); gp2.x = dpp_shr1_keep(hg2a, g2.x); gp2.y = dpp_shr1_keep(hg2b, g2.y);
;                     vp1.x = dpp_shr1_keep(hv1a, v3.x); vp1.y = dpp_shr1_keep(hv1b, v3.y); vp2.x = dpp_shr1_keep(hv2a, v2.x); vp2.y = dpp_shr1_keep(hv2b, v2.y);
;                     const f32x2 a0 = jp == 0 ? lo2(wg0) : hi2(wg0), a1 = jp == 0 ? lo2(wg1) : hi2(wg1), a2 = jp == 0 ? lo2(wg2) : hi2(wg2), ab = jp == 0 ? lo2(bg) : hi2(bg);
;                     const f32x2 c0 = jp == 0 ? lo2(wv0) : hi2(wv0), c1 = jp == 0 ? lo2(wv1) : hi2(wv1), c2 = jp == 0 ? lo2(wv2) : hi2(wv2), cb_ = jp == 0 ? lo2(bv) : hi2(bv);
;                     const f32x2 yg0 = ab + a0 * gp2 + a1 * gp1 + a2 * g0, yv0 = cb_ + c0 * vp2 + c1 * vp1 + c2 * v0;
;                     const f32x2 yg1 = ab + a0 * gp1 + a1 * g0 + a2 * g1, yv1 = cb_ + c0 * vp1 + c1 * v0 + c2 * v1;
;                     const f32x2 yg2 = ab + a0 * g0 + a1 * g1 + a2 * g2, yv2 = cb_ + c0 * v0 + c1 * v1 + c2 * v2;
;                     const f32x2 yg3 = ab + a0 * g1 + a1 * g2 + a2 * g3, yv3 = cb_ + c0 * v1 + c1 * v2 + c2 * v3;
;                     const f32x2 r0 = gelu_tanh_fast2(yg0) * yv0, r1 = gelu_tanh_fast2(yg1) * yv1, r2 = gelu_tanh_fast2(yg2) * yv2, r3 = gelu_tanh_fast2(yg3) * yv3;
	v_pk_fma_f32 v[186:187], v[186:187], v[130:131], v[146:147]
	v_pk_mul_f32 v[150:151], v[176:177], v[150:151]
	v_pk_fma_f32 v[186:187], v[182:183], v[134:135], v[186:187]
	v_exp_f32_e32 v150, v150
	v_exp_f32_e32 v151, v151
	v_pk_fma_f32 v[186:187], v[178:179], v[138:139], v[186:187]
	v_pk_fma_f32 v[228:229], v[182:183], v[138:139], v[228:229]
	v_pk_fma_f32 v[182:183], v[182:183], v[130:131], v[146:147]
	v_pk_add_f32 v[150:151], v[150:151], 1.0 op_sel_hi:[1,0]
	v_pk_fma_f32 v[178:179], v[178:179], v[134:135], v[182:183]
	v_rcp_f32_e32 v150, v150
	v_rcp_f32_e32 v151, v151
	v_pk_fma_f32 v[174:175], v[174:175], v[138:139], v[178:179]
	v_pk_mul_f32 v[158:159], v[228:229], v[228:229]
	v_cvt_pk_bf16_f32 v156, v156, v157
	v_pk_fma_f32 v[150:151], v[176:177], v[150:151], v[176:177] neg_lo:[1,0,0] neg_hi:[1,0,0]
	v_pk_mul_f32 v[176:177], v[186:187], v[186:187]
	v_pk_fma_f32 v[158:159], v[158:159], s[20:21], v[172:173] op_sel_hi:[1,0,0]
	v_pk_fma_f32 v[176:177], v[176:177], s[20:21], v[172:173] op_sel_hi:[1,0,0]
	v_pk_mul_f32 v[158:159], v[228:229], v[158:159]
	v_pk_mul_f32 v[176:177], v[186:187], v[176:177]
	v_exp_f32_e32 v158, v158
	v_exp_f32_e32 v176, v176
	v_exp_f32_e32 v177, v177
	v_exp_f32_e32 v159, v159
	v_pk_mul_f32 v[150:151], v[184:185], v[150:151]
	v_cvt_pk_bf16_f32 v140, v140, v141
	v_pk_add_f32 v[176:177], v[176:177], 1.0 op_sel_hi:[1,0]
	v_pk_add_f32 v[158:159], v[158:159], 1.0 op_sel_hi:[1,0]
	v_rcp_f32_e32 v176, v176
	v_rcp_f32_e32 v177, v177
	v_rcp_f32_e32 v158, v158
	v_rcp_f32_e32 v159, v159
	v_cvt_pk_bf16_f32 v165, v150, v151
	v_pk_fma_f32 v[176:177], v[186:187], v[176:177], v[186:187] neg_lo:[1,0,0] neg_hi:[1,0,0]
	v_pk_fma_f32 v[158:159], v[228:229], v[158:159], v[228:229] neg_lo:[1,0,0] neg_hi:[1,0,0]
	v_pk_mul_f32 v[166:167], v[166:167], v[176:177]
	v_pk_mul_f32 v[176:177], v[174:175], v[174:175]
	v_pk_mul_f32 v[158:159], v[180:181], v[158:159]
	v_pk_fma_f32 v[176:177], v[176:177], s[20:21], v[172:173] op_sel_hi:[1,0,0]
	v_cvt_pk_bf16_f32 v157, v158, v159
	v_cvt_pk_bf16_f32 v149, v166, v167
	s_nop 0
	v_pk_mul_f32 v[176:177], v[174:175], v[176:177]
	s_nop 0
	v_exp_f32_e32 v176, v176
	v_exp_f32_e32 v177, v177
	s_nop 0
	v_pk_add_f32 v[176:177], v[176:177], 1.0 op_sel_hi:[1,0]
	s_nop 0
	v_rcp_f32_e32 v176, v176
	v_rcp_f32_e32 v177, v177
	s_nop 0
	v_pk_fma_f32 v[174:175], v[174:175], v[176:177], v[174:175] neg_lo:[1,0,0] neg_hi:[1,0,0]
	s_nop 0
	v_pk_mul_f32 v[142:143], v[142:143], v[174:175]
	s_nop 0
	v_cvt_pk_bf16_f32 v141, v142, v143
	ds_read2_b32 v[142:143], v223 offset0:32 offset1:36
	ds_read2_b32 v[150:151], v223 offset0:40 offset1:44
	ds_read2_b32 v[158:159], v223 offset0:96 offset1:100
	ds_read2_b32 v[166:167], v223 offset0:104 offset1:108
	s_waitcnt lgkmcnt(3)
	v_mov_b32_dpp v143, v80 row_shr:1 row_mask:0xf bank_mask:0xf
	s_waitcnt lgkmcnt(2)
	v_mov_b32_dpp v150, v85 row_shr:1 row_mask:0xf bank_mask:0xf
	v_mov_b32_dpp v151, v81 row_shr:1 row_mask:0xf bank_mask:0xf
	v_mov_b32_e32 v174, v143
	v_mov_b32_dpp v142, v84 row_shr:1 row_mask:0xf bank_mask:0xf
	v_mov_b32_e32 v143, v150
	v_mov_b32_e32 v175, v151
	s_waitcnt lgkmcnt(1)
	v_mov_b32_dpp v159, v64 row_shr:1 row_mask:0xf bank_mask:0xf
	s_waitcnt lgkmcnt(0)
	v_mov_b32_dpp v167, v65 row_shr:1 row_mask:0xf bank_mask:0xf
	v_mov_b32_dpp v166, v69 row_shr:1 row_mask:0xf bank_mask:0xf
	v_pk_fma_f32 v[142:143], v[96:97], v[142:143], v[108:109]
	v_mov_b32_e32 v150, v159
	v_mov_b32_e32 v151, v167
	v_mov_b32_e32 v159, v166
	v_pk_fma_f32 v[142:143], v[100:101], v[174:175], v[142:143]
	v_pk_fma_f32 v[166:167], v[96:97], v[174:175], v[108:109]
	v_pk_fma_f32 v[142:143], v[92:93], v[104:105], v[142:143]
	v_pk_fma_f32 v[166:167], v[92:93], v[100:101], v[166:167]
	v_pk_fma_f32 v[92:93], v[92:93], v[96:97], v[108:109]
	v_pk_fma_f32 v[166:167], v[88:89], v[104:105], v[166:167]
	v_pk_fma_f32 v[92:93], v[88:89], v[100:101], v[92:93]
	v_pk_fma_f32 v[88:89], v[88:89], v[96:97], v[108:109]
	v_pk_fma_f32 v[92:93], v[84:85], v[104:105], v[92:93]
	v_pk_fma_f32 v[84:85], v[84:85], v[100:101], v[88:89]
	v_mov_b32_dpp v158, v68 row_shr:1 row_mask:0xf bank_mask:0xf
	v_pk_fma_f32 v[80:81], v[80:81], v[104:105], v[84:85]
	v_pk_mul_f32 v[84:85], v[92:93], v[92:93]
	v_pk_fma_f32 v[158:159], v[116:117], v[158:159], v[124:125]
	v_pk_fma_f32 v[84:85], v[84:85], s[20:21], v[172:173] op_sel_hi:[1,0,0]
	v_pk_fma_f32 v[158:159], v[120:121], v[150:151], v[158:159]
	v_pk_mul_f32 v[84:85], v[92:93], v[84:85]
	v_pk_fma_f32 v[150:151], v[116:117], v[150:151], v[124:125]
	v_exp_f32_e32 v84, v84
	v_exp_f32_e32 v85, v85
	v_pk_fma_f32 v[158:159], v[76:77], v[112:113], v[158:159]
	v_pk_fma_f32 v[150:151], v[76:77], v[120:121], v[150:151]
	v_pk_fma_f32 v[76:77], v[76:77], v[116:117], v[124:125]
	v_pk_add_f32 v[84:85], v[84:85], 1.0 op_sel_hi:[1,0]
	v_pk_fma_f32 v[150:151], v[72:73], v[112:113], v[150:151]
	v_rcp_f32_e32 v84, v84
	v_rcp_f32_e32 v85, v85
	v_pk_fma_f32 v[76:77], v[72:73], v[120:121], v[76:77]
	v_pk_fma_f32 v[72:73], v[72:73], v[116:117], v[124:125]
	v_pk_fma_f32 v[76:77], v[68:69], v[112:113], v[76:77]
	v_pk_fma_f32 v[68:69], v[68:69], v[120:121], v[72:73]
	v_pk_fma_f32 v[84:85], v[92:93], v[84:85], v[92:93] neg_lo:[1,0,0] neg_hi:[1,0,0]
	v_pk_fma_f32 v[64:65], v[64:65], v[112:113], v[68:69]
	v_pk_mul_f32 v[68:69], v[142:143], v[142:143]
	v_pk_mul_f32 v[72:73], v[166:167], v[166:167]
	v_pk_mul_f32 v[76:77], v[76:77], v[84:85]
	v_pk_mul_f32 v[84:85], v[80:81], v[80:81]
	v_pk_fma_f32 v[68:69], v[68:69], s[20:21], v[172:173] op_sel_hi:[1,0,0]
	v_pk_fma_f32 v[72:73], v[72:73], s[20:21], v[172:173] op_sel_hi:[1,0,0]
	v_pk_fma_f32 v[84:85], v[84:85], s[20:21], v[172:173] op_sel_hi:[1,0,0]
	v_pk_mul_f32 v[68:69], v[142:143], v[68:69]
; __device__ __forceinline__ unsigned cvt_pk_bf16(float lo, float hi) { unsigned r; asm("v_cvt_pk_bf16_f32 %0, %1, %2" : "=v"(r) : "v"(lo), "v"(hi)); return r; }
;     __device__ __forceinline__ void operator()(const f32x4 (&acc)[2][2][4][2], const Unit& u, int wr, int wc, int fr, int fq) const {
;     ...
;                     gp1.x = dpp_shr1_keep(hg1a, g3.x); gp1.y = dpp_shr1_keep(hg1b, g3.y); gp2.x = dpp_shr1_keep(hg2a, g2.x); gp2.y = dpp_shr1_keep(hg2b, g2.y);
;                     vp1.x = dpp_shr1_keep(hv1a, v3.x); vp1.y = dpp_shr1_keep(hv1b, v3.y); vp2.x = dpp_shr1_keep(hv2a, v2.x); vp2.y = dpp_shr1_keep(hv2b, v2.y);
;                     const f32x2 a0 = jp == 0 ? lo2(wg0) : hi2(wg0), a1 = jp == 0 ? lo2(wg1) : hi2(wg1), a2 = jp == 0 ? lo2(wg2) : hi2(wg2), ab = jp == 0 ? lo2(bg) : hi2(bg);
;                     const f32x2 c0 = jp == 0 ? lo2(wv0) : hi2(wv0), c1 = jp == 0 ? lo2(wv1) : hi2(wv1), c2 = jp == 0 ? lo2(wv2) : hi2(wv2), cb_ = jp == 0 ? lo2(bv) : hi2(bv);
;                     const f32x2 yg0 = ab + a0 * gp2 + a1 * gp1 + a2 * g0, yv0 = cb_ + c0 * vp2 + c1 * vp1 + c2 * v0;
;                     const f32x2 yg1 = ab + a0 * gp1 + a1 * g0 + a2 * g1, yv1 = cb_ + c0 * vp1 + c1 * v0 + c2 * v1;
;                     const f32x2 yg2 = ab + a0 * g0 + a1 * g1 + a2 * g2, yv2 = cb_ + c0 * v0 + c1 * v1 + c2 * v2;
;                     const f32x2 yg3 = ab + a0 * g1 + a1 * g2 + a2 * g3, yv3 = cb_ + c0 * v1 + c1 * v2 + c2 * v3;
;                     const f32x2 r0 = gelu_tanh_fast2(yg0) * yv0, r1 = gelu_tanh_fast2(yg1) * yv1, r2 = gelu_tanh_fast2(yg2) * yv2, r3 = gelu_tanh_fast2(yg3) * yv3;
;                     const unsigned q0 = cvt_pk_bf16(r0.x, r0.y), q1 = cvt_pk_bf16(r1.x, r1.y), q2 = cvt_pk_bf16(r2.x, r2.y), q3 = cvt_pk_bf16(r3.x, r3.y);
;                     if (jp == 0) { pk[0][n].x = q0; pk[1][n].x = q1; pk[2][n].x = q2; pk[3][n].x = q3; } else { pk[0][n].y = q0; pk[1][n].y = q1; pk[2][n].y = q2; pk[3][n].y = q3; }
;                 }
;             }
;             bf16_t* op = ACT + (size_t)(tok0 + ai * HALF) * DFF + ch0;
;             const bool top = (ai == 0) && (wr == 0) && (fr == 0);
; #pragma unroll
;             for (int m = 0; m < 4; ++m) { const u32x4 w = (u32x4){pk[m][0].x, pk[m][0].y, pk[m][1].x, pk[m][1].y};
;                 if (!(top && m < 2)) *(u32x4*)(op + (size_t)m * DFF) = w; }
	v_pk_mul_f32 v[72:73], v[166:167], v[72:73]
	v_pk_mul_f32 v[84:85], v[80:81], v[84:85]
	v_exp_f32_e32 v68, v68
	v_exp_f32_e32 v69, v69
	v_exp_f32_e32 v72, v72
	v_exp_f32_e32 v73, v73
	v_exp_f32_e32 v84, v84
	v_exp_f32_e32 v85, v85
	v_pk_add_f32 v[68:69], v[68:69], 1.0 op_sel_hi:[1,0]
	v_pk_add_f32 v[72:73], v[72:73], 1.0 op_sel_hi:[1,0]
	v_rcp_f32_e32 v68, v68
	v_pk_add_f32 v[84:85], v[84:85], 1.0 op_sel_hi:[1,0]
	v_rcp_f32_e32 v69, v69
	v_rcp_f32_e32 v72, v72
	v_rcp_f32_e32 v73, v73
	v_rcp_f32_e32 v84, v84
	v_rcp_f32_e32 v85, v85
	v_pk_fma_f32 v[68:69], v[142:143], v[68:69], v[142:143] neg_lo:[1,0,0] neg_hi:[1,0,0]
	v_pk_fma_f32 v[72:73], v[166:167], v[72:73], v[166:167] neg_lo:[1,0,0] neg_hi:[1,0,0]
	v_pk_mul_f32 v[68:69], v[158:159], v[68:69]
	v_pk_fma_f32 v[80:81], v[80:81], v[84:85], v[80:81] neg_lo:[1,0,0] neg_hi:[1,0,0]
	v_pk_mul_f32 v[72:73], v[150:151], v[72:73]
	v_pk_mul_f32 v[64:65], v[64:65], v[80:81]
	v_cvt_pk_bf16_f32 v166, v68, v69
	v_cvt_pk_bf16_f32 v158, v72, v73
	v_cvt_pk_bf16_f32 v150, v76, v77
	v_pk_fma_f32 v[84:85], v[90:91], v[98:99], v[110:111]
	v_cvt_pk_bf16_f32 v142, v64, v65
	ds_read2_b32 v[64:65], v223 offset0:48 offset1:52
	ds_read2_b32 v[68:69], v223 offset0:56 offset1:60
	ds_read2_b32 v[72:73], v223 offset0:112 offset1:116
	ds_read2_b32 v[76:77], v223 offset0:120 offset1:124
	v_pk_fma_f32 v[84:85], v[86:87], v[102:103], v[84:85]
	s_waitcnt lgkmcnt(3)
	v_mov_b32_dpp v65, v82 row_shr:1 row_mask:0xf bank_mask:0xf
	s_waitcnt lgkmcnt(2)
	v_mov_b32_dpp v68, v87 row_shr:1 row_mask:0xf bank_mask:0xf
	s_waitcnt lgkmcnt(1)
	v_mov_b32_dpp v73, v66 row_shr:1 row_mask:0xf bank_mask:0xf
	s_waitcnt lgkmcnt(0)
	v_mov_b32_dpp v76, v71 row_shr:1 row_mask:0xf bank_mask:0xf
	v_mov_b32_dpp v69, v83 row_shr:1 row_mask:0xf bank_mask:0xf
	v_mov_b32_e32 v80, v65
	v_mov_b32_e32 v65, v68
	v_mov_b32_dpp v77, v67 row_shr:1 row_mask:0xf bank_mask:0xf
	v_mov_b32_e32 v68, v73
	v_mov_b32_dpp v72, v70 row_shr:1 row_mask:0xf bank_mask:0xf
	v_mov_b32_e32 v73, v76
	v_mov_b32_e32 v81, v69
	v_mov_b32_e32 v69, v77
	v_pk_fma_f32 v[72:73], v[118:119], v[72:73], v[126:127]
	v_mov_b32_dpp v64, v86 row_shr:1 row_mask:0xf bank_mask:0xf
	v_pk_fma_f32 v[72:73], v[122:123], v[68:69], v[72:73]
	v_pk_fma_f32 v[68:69], v[118:119], v[68:69], v[126:127]
	v_pk_fma_f32 v[64:65], v[98:99], v[64:65], v[110:111]
	v_pk_fma_f32 v[72:73], v[78:79], v[114:115], v[72:73]
	v_pk_fma_f32 v[68:69], v[78:79], v[122:123], v[68:69]
	v_pk_fma_f32 v[78:79], v[78:79], v[118:119], v[126:127]
	v_pk_fma_f32 v[64:65], v[102:103], v[80:81], v[64:65]
	v_pk_fma_f32 v[68:69], v[74:75], v[114:115], v[68:69]
	v_pk_fma_f32 v[78:79], v[74:75], v[122:123], v[78:79]
	v_pk_fma_f32 v[74:75], v[74:75], v[118:119], v[126:127]
	v_pk_fma_f32 v[64:65], v[94:95], v[106:107], v[64:65]
	v_pk_fma_f32 v[78:79], v[70:71], v[114:115], v[78:79]
	v_pk_fma_f32 v[70:71], v[70:71], v[122:123], v[74:75]
	v_pk_fma_f32 v[76:77], v[98:99], v[80:81], v[110:111]
	v_pk_fma_f32 v[66:67], v[66:67], v[114:115], v[70:71]
	v_pk_mul_f32 v[70:71], v[64:65], v[64:65]
	v_pk_fma_f32 v[76:77], v[94:95], v[102:103], v[76:77]
	v_pk_fma_f32 v[70:71], v[70:71], s[20:21], v[172:173] op_sel_hi:[1,0,0]
	v_pk_fma_f32 v[76:77], v[90:91], v[106:107], v[76:77]
	v_pk_mul_f32 v[70:71], v[64:65], v[70:71]
	v_pk_fma_f32 v[80:81], v[94:95], v[98:99], v[110:111]
	v_exp_f32_e32 v70, v70
	v_exp_f32_e32 v71, v71
	v_pk_fma_f32 v[80:81], v[90:91], v[102:103], v[80:81]
	v_pk_fma_f32 v[82:83], v[82:83], v[106:107], v[84:85]
	v_pk_fma_f32 v[80:81], v[86:87], v[106:107], v[80:81]
	v_pk_add_f32 v[70:71], v[70:71], 1.0 op_sel_hi:[1,0]
	s_nop 0
	v_rcp_f32_e32 v70, v70
	v_rcp_f32_e32 v71, v71
	s_nop 0
	v_pk_fma_f32 v[64:65], v[64:65], v[70:71], v[64:65] neg_lo:[1,0,0] neg_hi:[1,0,0]
	v_pk_mul_f32 v[70:71], v[76:77], v[76:77]
	v_pk_mul_f32 v[64:65], v[72:73], v[64:65]
	v_pk_fma_f32 v[70:71], v[70:71], s[20:21], v[172:173] op_sel_hi:[1,0,0]
	v_pk_mul_f32 v[72:73], v[82:83], v[82:83]
	v_pk_mul_f32 v[70:71], v[76:77], v[70:71]
	v_pk_fma_f32 v[72:73], v[72:73], s[20:21], v[172:173] op_sel_hi:[1,0,0]
	v_exp_f32_e32 v70, v70
	v_exp_f32_e32 v71, v71
	v_pk_mul_f32 v[72:73], v[82:83], v[72:73]
	v_cvt_pk_bf16_f32 v167, v64, v65
	v_mov_b64_e32 v[64:65], s[82:83]
	v_pk_add_f32 v[70:71], v[70:71], 1.0 op_sel_hi:[1,0]
	v_exp_f32_e32 v72, v72
	v_rcp_f32_e32 v70, v70
	v_rcp_f32_e32 v71, v71
	v_exp_f32_e32 v73, v73
	v_pk_fma_f32 v[70:71], v[76:77], v[70:71], v[76:77] neg_lo:[1,0,0] neg_hi:[1,0,0]
	s_nop 0
	v_pk_mul_f32 v[68:69], v[68:69], v[70:71]
	v_pk_mul_f32 v[70:71], v[80:81], v[80:81]
	v_pk_add_f32 v[72:73], v[72:73], 1.0 op_sel_hi:[1,0]
	v_pk_fma_f32 v[70:71], v[70:71], s[20:21], v[172:173] op_sel_hi:[1,0,0]
	v_rcp_f32_e32 v72, v72
	v_pk_mul_f32 v[70:71], v[80:81], v[70:71]
	v_rcp_f32_e32 v73, v73
	v_exp_f32_e32 v70, v70
	v_exp_f32_e32 v71, v71
	v_mad_i64_i32 v[64:65], s[20:21], v226, s73, v[64:65]
	v_pk_fma_f32 v[72:73], v[82:83], v[72:73], v[82:83] neg_lo:[1,0,0] neg_hi:[1,0,0]
	v_pk_add_f32 v[70:71], v[70:71], 1.0 op_sel_hi:[1,0]
	v_lshl_add_u64 v[64:65], v[220:221], 1, v[64:65]
	v_rcp_f32_e32 v70, v70
	v_rcp_f32_e32 v71, v71
	v_pk_mul_f32 v[66:67], v[66:67], v[72:73]
	v_cvt_pk_bf16_f32 v159, v68, v69
	v_pk_fma_f32 v[70:71], v[80:81], v[70:71], v[80:81] neg_lo:[1,0,0] neg_hi:[1,0,0]
	s_nop 0
	v_pk_mul_f32 v[70:71], v[78:79], v[70:71]
	v_cvt_pk_bf16_f32 v143, v66, v67
	s_nop 0
	v_cvt_pk_bf16_f32 v151, v70, v71
	s_and_saveexec_b64 s[20:21], s[44:45]
	s_cbranch_execz .LBB0_539
	v_add_co_u32_e32 v66, vcc, 0x2000, v64
	global_store_dwordx4 v[64:65], v[164:167], off
	s_nop 0
	v_addc_co_u32_e32 v67, vcc, 0, v65, vcc
	global_store_dwordx4 v[66:67], v[156:159], off offset:3072
